# v5: grid barriers 2,4,5 split into arrive/wait halves with independent work (passA gate-scan prologue, phase-5 first K-loop, phase-6 first K-loop) in between; WgT staging loads in flight
# speedup vs baseline: 1.0267x; 1.0267x over previous
; __device__ __forceinline__ unsigned xb_ld(unsigned* p)              { return __hip_atomic_load(p, __ATOMIC_RELAXED, __HIP_MEMORY_SCOPE_AGENT); }
; __device__ __forceinline__ unsigned xb_add(unsigned* p, unsigned v) { return __hip_atomic_fetch_add(p, v, __ATOMIC_RELAXED, __HIP_MEMORY_SCOPE_AGENT); }
; __device__ __forceinline__ void xcd_barrier_complete(unsigned* bar, unsigned x, unsigned& nloc, unsigned& nx) {
;     const unsigned G = gridDim.x * gridDim.y * gridDim.z;
;     unsigned sum, cnt, mine, sp = 0u;
;     for (;;) {
;         sum = 0u; cnt = 0u; mine = 0u;
; #pragma unroll
;         for (unsigned j = 0; j < 16; ++j) { const unsigned c = xb_ld(&bar[XB_XCNT(j)]); sum += c; cnt += (c > 0u) ? 1u : 0u; mine = (j == x) ? c : mine; }
;         if (sum == G) break;
;         __builtin_amdgcn_s_sleep(1);
;         if ((++sp & 255u) == 0u) { if (xb_ld(&bar[XB_TMO])) break; if (sp > XB_SPIN_CAP) { atomicAdd(&bar[XB_TMO], 1u); break; } }
;     }
;     nloc = mine > 0u ? mine : 1u; nx = cnt > 0u ? cnt : 1u;
; }
; __device__ __forceinline__ void xcd_barrier(const XcdBarrier& b) {
;     asm volatile("s_waitcnt vmcnt(0)" ::: "memory");
;     __syncthreads();
;     if (threadIdx.x == 0) {
;         unsigned* bar = b.bar;
;         __builtin_amdgcn_s_waitcnt(0);
;         unsigned nloc = b.st[0], nx = b.st[1];
;         if (nloc == 0u) { xcd_barrier_complete(bar, b.x, nloc, nx); b.st[0] = nloc; b.st[1] = nx; }
;         const unsigned old = xb_add(&bar[XB_XSUB(b.x)], 1u);
;         const unsigned gen = old / nloc;
;         if (old + 1u == (gen + 1u) * nloc) {
;             __builtin_amdgcn_fence(__ATOMIC_RELEASE, "agent");
;             asm volatile("s_waitcnt vmcnt(0)" ::: "memory");
;             const unsigned og = xb_add(&bar[XB_TOP], 1u);
;             const unsigned tg = og / nx;
;             if (og + 1u == (tg + 1u) * nx) xb_add(&bar[XB_TOPGEN], 1u);
;             else XB_SPIN(xb_ld(&bar[XB_TOPGEN]) == tg, bar);
;             __builtin_amdgcn_fence(__ATOMIC_ACQUIRE, "agent");
;             xb_add(&bar[XB_XGEN(b.x)], 1u);
;             asm volatile("s_waitcnt vmcnt(0)" ::: "memory");
;         } else {
;             XB_SPIN(xb_ld(&bar[XB_XGEN(b.x)]) == gen, bar);
;             __builtin_amdgcn_fence(__ATOMIC_ACQUIRE, "agent");
;             asm volatile("s_waitcnt vmcnt(0)" ::: "memory");
;         }
.LBB0_336:
	s_or_b64 exec, exec, s[8:9]
	v_cvt_f32_u32_e32 v4, v2
	s_waitcnt vmcnt(0)
	v_readfirstlane_b32 s6, v3
	v_sub_u32_e32 v3, 0, v2
	v_rcp_iflag_f32_e32 v4, v4
	v_add_u32_e32 v5, s6, v1
	v_mul_f32_e32 v4, 0x4f7ffffe, v4
	v_cvt_u32_f32_e32 v4, v4
	v_mul_lo_u32 v1, v3, v4
	v_mul_hi_u32 v1, v4, v1
	v_add_u32_e32 v1, v4, v1
	v_mul_hi_u32 v1, v5, v1
	v_mul_lo_u32 v3, v1, v2
	v_sub_u32_e32 v3, v5, v3
	v_add_u32_e32 v4, 1, v1
	v_cmp_ge_u32_e32 vcc, v3, v2
	s_nop 1
	v_cndmask_b32_e32 v1, v1, v4, vcc
	v_sub_u32_e32 v4, v3, v2
	v_cndmask_b32_e32 v3, v3, v4, vcc
	v_add_u32_e32 v4, 1, v1
	v_cmp_ge_u32_e32 vcc, v3, v2
	v_add_u32_e32 v3, 1, v5
	s_nop 0
	v_cndmask_b32_e32 v1, v1, v4, vcc
	v_mul_lo_u32 v4, v2, v1
	v_add_u32_e32 v2, v4, v2
	v_cmp_ne_u32_e32 vcc, v3, v2
	s_and_saveexec_b64 s[6:7], vcc
	s_xor_b64 s[6:7], exec, s[6:7]
	s_cbranch_execz .LBB0_350
.LBB0_350:
	s_andn2_saveexec_b64 s[6:7], s[6:7]
	s_cbranch_execz .LBB0_370
	s_mov_b64 s[6:7], exec
	buffer_wbl2 sc1
	s_waitcnt lgkmcnt(0)
	s_waitcnt vmcnt(0)
	v_mbcnt_lo_u32_b32 v1, s6, 0
	v_mbcnt_hi_u32_b32 v1, s7, v1
	v_cmp_eq_u32_e32 vcc, 0, v1
	s_and_saveexec_b64 s[8:9], vcc
	s_cbranch_execz .LBB0_353
	s_bcnt1_i32_b64 s6, s[6:7]
	v_mov_b32_e32 v2, 0xff83000
	v_mov_b32_e32 v3, s6
	global_atomic_add v2, v2, v3, s[70:71] offset:1024 sc0
.LBB0_353:
	s_or_b64 exec, exec, s[8:9]
	v_cvt_f32_u32_e32 v3, v0
	s_waitcnt vmcnt(0)
	v_readfirstlane_b32 s6, v2
	s_add_u32 s8, s70, 0xff83500
	s_addc_u32 s9, s71, 0
	v_rcp_iflag_f32_e32 v3, v3
	v_add_u32_e32 v1, s6, v1
	v_add_u32_e32 v4, 1, v1
	s_mov_b64 s[10:11], -1
	v_mul_f32_e32 v2, 0x4f7ffffe, v3
	v_cvt_u32_f32_e32 v2, v2
	v_sub_u32_e32 v3, 0, v0
	v_mul_lo_u32 v3, v3, v2
	v_mul_hi_u32 v3, v2, v3
	v_add_u32_e32 v2, v2, v3
	v_mul_hi_u32 v2, v1, v2
	v_mul_lo_u32 v3, v2, v0
	v_sub_u32_e32 v1, v1, v3
	v_add_u32_e32 v5, 1, v2
	v_cmp_ge_u32_e32 vcc, v1, v0
	v_sub_u32_e32 v3, v1, v0
	s_nop 0
	v_cndmask_b32_e32 v2, v2, v5, vcc
	v_cndmask_b32_e32 v1, v1, v3, vcc
	v_add_u32_e32 v3, 1, v2
	v_cmp_ge_u32_e32 vcc, v1, v0
	s_nop 1
	v_cndmask_b32_e32 v2, v2, v3, vcc
	v_mul_lo_u32 v1, v0, v2
	v_add_u32_e32 v0, v1, v0
	v_cmp_ne_u32_e32 vcc, v4, v0
	v_mov_b64_e32 v[0:1], s[8:9]
	s_and_saveexec_b64 s[6:7], vcc
	s_cbranch_execz .LBB0_365
	s_andn2_b64 s[10:11], s[10:11], exec

; __device__ __forceinline__ unsigned xb_ld(unsigned* p)              { return __hip_atomic_load(p, __ATOMIC_RELAXED, __HIP_MEMORY_SCOPE_AGENT); }
; __device__ __forceinline__ unsigned xb_add(unsigned* p, unsigned v) { return __hip_atomic_fetch_add(p, v, __ATOMIC_RELAXED, __HIP_MEMORY_SCOPE_AGENT); }
; #define XB_SPIN(cond, bar) do { unsigned _sp = 0; while (cond) { __builtin_amdgcn_s_sleep(1); \
;     if ((++_sp & 255u) == 0u) { if (xb_ld(&(bar)[XB_TMO])) break; if (_sp > XB_SPIN_CAP) { atomicAdd(&(bar)[XB_TMO], 1u); break; } } } } while (0)
; __device__ __forceinline__ void xcd_barrier(const XcdBarrier& b) {
;     ...
;             __builtin_amdgcn_fence(__ATOMIC_RELEASE, "agent");
;             asm volatile("s_waitcnt vmcnt(0)" ::: "memory");
;             const unsigned og = xb_add(&bar[XB_TOP], 1u);
;             const unsigned tg = og / nx;
;             if (og + 1u == (tg + 1u) * nx) xb_add(&bar[XB_TOPGEN], 1u);
;             else XB_SPIN(xb_ld(&bar[XB_TOPGEN]) == tg, bar);
;             __builtin_amdgcn_fence(__ATOMIC_ACQUIRE, "agent");
;             xb_add(&bar[XB_XGEN(b.x)], 1u);
;             asm volatile("s_waitcnt vmcnt(0)" ::: "memory");
.LBB0_367:
	s_or_b64 exec, exec, s[6:7]
	s_mov_b64 s[6:7], exec
	v_mbcnt_lo_u32_b32 v0, s6, 0
	v_mbcnt_hi_u32_b32 v0, s7, v0
	v_cmp_eq_u32_e32 vcc, 0, v0
	s_waitcnt vmcnt(0)
	s_and_saveexec_b64 s[8:9], vcc
	s_cbranch_execz .LBB0_369
	s_bcnt1_i32_b64 s6, s[6:7]
	v_mov_b32_e32 v0, 0x2000
	v_mov_b32_e32 v1, s6
	global_atomic_add v0, v1, s[4:5] offset:1024

; #define LAS __attribute__((address_space(3)))
; __device__ __forceinline__ int opaque_tid() { int t = (int)threadIdx.x; asm volatile("" : "+v"(t)); return t; }
; __device__ void passA(const Params& p, LAS unsigned char* lds, int wg) {
;     const int tid = opaque_tid(), wid = tid >> 6, lane = tid & 63, fr = lane & 15, fq = lane >> 4;
;     const int sid = wg >> 2, vs = wg & 3; const int b = sid >> 3, h = (sid >> 1) & 3, dir = sid & 1;
;     LAS bf16_t* Kt = (LAS bf16_t*)lds;
;     LAS bf16_t* Ve = Kt + 256 * 136;
;     LAS float* eA = (LAS float*)(lds + 87040);
;     LAS float* bendA = eA + 18 * 128; LAS float* maxwA = bendA + 32; LAS float* decayA = maxwA + 32; LAS float* mprevA = decayA + 32; LAS float* mnewA = mprevA + 32;
;     LAS bf16_t* eB = (LAS bf16_t*)(mnewA + 32);
;     const float* GL = (const float*)(p.ws + OFF_GL); const float* GC = (const float*)(p.ws + OFF_GC);
;     for (int st = wid; st < 18; st += 8) {
;         const bool isctx = st < 2; const int ci = isctx ? (dir ? 1 - st : st) : (dir ? 15 - (st - 2) : st - 2);
;         const int T = isctx ? 256 : 2048; const float* G = isctx ? GC + (size_t)b * 16 * 256 : GL + (size_t)b * 16 * 2048;
;         const float* pli = G + (size_t)(dir * 8 + h) * T + ci * 128; const float* plf = G + (size_t)(dir * 8 + 4 + h) * T + ci * 128;
;         const int s0 = dir ? 127 - 2 * lane : 2 * lane, s1 = dir ? 126 - 2 * lane : 2 * lane + 1;
;         const float lf0 = plf[s0], lf1 = plf[s1], li0 = pli[s0], li1 = pli[s1];
.LBB0_370:
	s_or_b64 exec, exec, s[0:1]
	s_and_b32 s24, s2, 7
	s_ashr_i32 s0, s2, 3
	s_lshl_b32 s29, s24, 5
	s_and_b32 s1, s0, -4
	v_mov_b32_e32 v104, v224
	s_add_i32 s29, s29, s1
	v_mov_b32_e32 v4, v224
	s_waitcnt lgkmcnt(0)
	s_ashr_i32 s26, s29, 2
	v_ashrrev_i32_e32 v56, 6, v4
	s_ashr_i32 s46, s29, 5
	s_bfe_u32 s25, s0, 0x20003
	s_and_b32 s28, s26, 1
	v_cmp_gt_i32_e32 vcc, 18, v56
	s_and_saveexec_b64 s[48:49], vcc
	s_cbranch_execz .LBB0_382
	v_and_b32_e32 v2, 63, v4
	s_cmp_eq_u32 s28, 0
	v_lshlrev_b32_e32 v1, 1, v2
	v_xor_b32_e32 v0, 0x7f, v1
	s_cselect_b64 s[0:1], -1, 0
	v_cndmask_b32_e64 v0, v0, v1, s[0:1]
	v_xor_b32_e32 v3, 0x7e, v1
	v_or_b32_e32 v1, 1, v1
	v_cndmask_b32_e64 v6, v3, v1, s[0:1]
	v_mbcnt_hi_u32_b32 v3, -1, v158
	v_and_b32_e32 v7, 64, v3
	v_add_u32_e32 v9, -1, v3
	v_cmp_lt_i32_e32 vcc, v9, v7
	s_cmp_lg_u32 s28, 0
	s_cselect_b64 s[14:15], -1, 0
	v_cndmask_b32_e32 v9, v9, v3, vcc
	v_lshlrev_b32_e32 v12, 2, v9
	v_add_u32_e32 v9, -2, v3
	v_cmp_lt_i32_e32 vcc, v9, v7
	s_ashr_i32 s47, s46, 31
	s_lshl_b64 s[4:5], s[46:47], 17
	v_cndmask_b32_e32 v9, v9, v3, vcc
	v_lshlrev_b32_e32 v13, 2, v9
	v_add_u32_e32 v9, -4, v3
	v_cmp_lt_i32_e32 vcc, v9, v7
	s_add_u32 s4, s70, s4
	s_addc_u32 s5, s71, s5
	v_cndmask_b32_e32 v9, v9, v3, vcc
	v_lshlrev_b32_e32 v14, 2, v9
	v_add_u32_e32 v9, -8, v3
	s_add_u32 s50, s4, 0xfc00000
	v_cmp_lt_i32_e32 vcc, v9, v7
	s_addc_u32 s51, s5, 0
	s_lshl_b64 s[4:5], s[46:47], 14
	v_cndmask_b32_e32 v9, v9, v3, vcc
	s_add_u32 s4, s70, s4
	v_lshlrev_b32_e32 v15, 2, v9
	v_add_u32_e32 v9, -16, v3
	s_addc_u32 s5, s71, s5
	v_cmp_lt_i32_e32 vcc, v9, v7
	s_add_u32 s52, s4, 0xfd00000
	s_addc_u32 s53, s5, 0
	v_cndmask_b32_e32 v9, v9, v3, vcc
	s_lshl_b32 s4, s28, 3
	v_lshlrev_b32_e32 v16, 2, v9
	v_subrev_u32_e32 v9, 32, v3
	s_or_b32 s38, s4, s25
	v_add_u32_e32 v8, 64, v7
	v_cmp_eq_u32_e64 s[16:17], 0, v2
	v_cmp_gt_u32_e64 s[4:5], 2, v2
	v_cmp_gt_u32_e64 s[6:7], 4, v2
	v_cmp_gt_u32_e64 s[8:9], 8, v2
	v_cmp_gt_u32_e64 s[10:11], 16, v2
	v_cmp_lt_i32_e32 vcc, v9, v7
	v_cmp_gt_u32_e64 s[12:13], 32, v2
	v_xor_b32_e32 v2, 32, v3
	v_cndmask_b32_e32 v7, v9, v3, vcc
	v_cmp_lt_i32_e32 vcc, v2, v8
	v_bfrev_b32_e32 v5, 0.5
	v_lshl_or_b32 v5, v3, 2, v5
	v_cndmask_b32_e32 v2, v3, v2, vcc
	v_lshlrev_b32_e32 v18, 2, v2
	v_xor_b32_e32 v2, 16, v3
	v_cmp_lt_i32_e32 vcc, v2, v8
	s_or_b32 s39, s38, 4
	v_mov_b32_e32 v1, 0
	v_cndmask_b32_e32 v2, v3, v2, vcc
	v_lshlrev_b32_e32 v19, 2, v2
	v_xor_b32_e32 v2, 8, v3
	v_cmp_lt_i32_e32 vcc, v2, v8
	v_lshlrev_b32_e32 v17, 2, v7
	v_sub_u32_e32 v24, 1, v56
	v_cndmask_b32_e32 v2, v3, v2, vcc
	v_lshlrev_b32_e32 v20, 2, v2
	v_xor_b32_e32 v2, 4, v3
	v_cmp_lt_i32_e32 vcc, v2, v8
	v_lshlrev_b32_e32 v25, 2, v56
	s_mov_b64 s[74:75], 0
	v_cndmask_b32_e32 v2, v3, v2, vcc
	v_lshlrev_b32_e32 v21, 2, v2
	v_xor_b32_e32 v2, 2, v3
	v_cmp_lt_i32_e32 vcc, v2, v8
	v_mov_b32_e32 v28, v56
	s_nop 0
	v_cndmask_b32_e32 v2, v3, v2, vcc
	v_lshlrev_b32_e32 v22, 2, v2
	v_xor_b32_e32 v2, 1, v3
	v_cmp_lt_i32_e32 vcc, v2, v8
	s_nop 1
	v_cndmask_b32_e32 v2, v3, v2, vcc
	v_lshlrev_b32_e32 v23, 2, v2
	v_lshlrev_b32_e32 v2, 9, v56
	v_lshl_or_b32 v3, v6, 2, v2
	v_lshl_or_b32 v2, v0, 2, v2
	v_add_u32_e32 v27, 0x15400, v2
	v_cndmask_b32_e64 v2, 0, 1, s[14:15]
	v_add_u32_e32 v26, 0x15400, v3
	v_cmp_ne_u32_e64 s[14:15], 1, v2
	v_lshlrev_b32_e32 v2, 2, v0
	v_lshlrev_b32_e32 v6, 2, v6
	s_branch .LBB0_373

; __device__ __forceinline__ unsigned xb_ld(unsigned* p)              { return __hip_atomic_load(p, __ATOMIC_RELAXED, __HIP_MEMORY_SCOPE_AGENT); }
; #define XB_SPIN(cond, bar) do { unsigned _sp = 0; while (cond) { __builtin_amdgcn_s_sleep(1); \
;     if ((++_sp & 255u) == 0u) { if (xb_ld(&(bar)[XB_TMO])) break; if (_sp > XB_SPIN_CAP) { atomicAdd(&(bar)[XB_TMO], 1u); break; } } } } while (0)
; __device__ __forceinline__ void passA_chunk(const Params& p, int st, int b, int h, int dir, int vs, bool& isctx, int& ci, const bf16_t*& Kbase, const bf16_t*& Vbase) {
;     isctx = st < 2;
;     if (isctx) { ci = dir ? 1 - st : st;
;         Kbase = (const bf16_t*)(p.ws + OFF_KC) + (size_t)((b * 2 + ci) * 4 + h) * 32768;
;         Vbase = (const bf16_t*)(p.ws + OFF_VTC) + (size_t)(b * 2 + ci) * 131072 + (h * 16 + vs * 4) * 2048; }
;     else { const int s2 = st - 2; ci = dir ? 15 - s2 : s2;
;         Kbase = (const bf16_t*)(p.ws + OFF_K) + (size_t)((b * 16 + ci) * 4 + h) * 32768;
;         Vbase = (const bf16_t*)(p.ws + OFF_VT) + (size_t)(b * 16 + ci) * 131072 + (h * 16 + vs * 4) * 2048; }
; }
; __device__ __forceinline__ void xcd_barrier(const XcdBarrier& b) {
;     ...
;             XB_SPIN(xb_ld(&bar[XB_XGEN(b.x)]) == gen, bar);
;             __builtin_amdgcn_fence(__ATOMIC_ACQUIRE, "agent");
;             asm volatile("s_waitcnt vmcnt(0)" ::: "memory");
.LBB0_390:
	s_or_b64 exec, exec, s[0:1]
	s_lshl_b32 s0, s46, 1
	s_or_b32 s8, s28, s0
	s_lshl_b32 s0, s8, 2
	s_or_b32 s0, s0, s25
	s_ashr_i32 s1, s0, 31
	s_lshl_b64 s[0:1], s[0:1], 16
	v_readlane_b32 s11, v254, 33
	s_add_u32 s0, s11, s0
	v_readlane_b32 s14, v254, 34
	s_addc_u32 s1, s14, s1
	s_ashr_i32 s9, s8, 31
	s_lshl_b64 s[6:7], s[8:9], 18
	s_add_u32 s6, s3, s6
	s_addc_u32 s7, s27, s7
	s_lshl_b32 s9, s34, 14
	s_lshl_b32 s10, s25, 16
	s_or_b32 s10, s10, s9
	s_add_u32 s6, s6, s10
	v_ashrrev_i32_e32 v5, 31, v4
	s_addc_u32 s7, s7, 0
	v_lshlrev_b64 v[80:81], 4, v[4:5]
	v_lshl_add_u64 v[0:1], s[6:7], 0, v[80:81]
	v_cmp_eq_u32_e32 vcc, 0, v224
	s_and_saveexec_b64 s[12:13], vcc
	s_cbranch_execz .Lgb2_done
	s_add_u32 s38, s70, 0xff83500
	s_addc_u32 s39, s71, 0
	s_mov_b32 s40, 0x8000
	v_mov_b32_e32 v250, 0
.Lgb2_spin:
	global_load_dword v251, v250, s[38:39] sc1
	s_waitcnt vmcnt(0)
	v_readfirstlane_b32 s41, v251
	s_cmp_ge_u32 s41, 2
	s_cbranch_scc1 .Lgb2_ok
	s_sleep 1
	s_sub_u32 s40, s40, 1
	s_cmp_lg_u32 s40, 0
	s_cbranch_scc1 .Lgb2_spin

; __device__ void passA(const Params& p, LAS unsigned char* lds, int wg) {
;     ...
;     { bool ic; int ci; const bf16_t* Kb; const bf16_t* Vb; passA_chunk(p, 0, b, h, dir, vs, ic, ci, Kb, Vb);
; #pragma unroll
;         for (int rep = 0; rep < 2; ++rep) { const int it = tid + rep * 512;
;             vr[rep] = *(const u32x4*)(Vb + (size_t)it * 8);
;             const int sq = (it & 15) | (((it >> 6) & 1) << 4), ko = ((it >> 4) & 3) | ((it >> 7) << 2); const bf16_t* src = Kb + (size_t)((sq >> 2) * 8 + (ko >> 2)) * 512 + ((sq & 3) * 16 + (ko & 3)) * 8;
;             kr[rep][0] = *(const u32x4*)src; kr[rep][1] = *(const u32x4*)(src + 32); kr[rep][2] = *(const u32x4*)(src + 64); kr[rep][3] = *(const u32x4*)(src + 96); } }
;     for (int st = 0; st < 18; ++st) {
;         bool isctx; int ci; const bf16_t* Kb; const bf16_t* Vb; passA_chunk(p, st, b, h, dir, vs, isctx, ci, Kb, Vb);
;         if (!isctx) {
;             bf16_t* cs = cst_ptr(p, sid, ci);
; #pragma unroll
;             for (int vt = 0; vt < 4; ++vt) { u32x4 w; w.x = cvt_pk_bf16(acc[0][vt][0], acc[0][vt][1]); w.y = cvt_pk_bf16(acc[0][vt][2], acc[0][vt][3]);
;                 w.z = cvt_pk_bf16(acc[1][vt][0], acc[1][vt][1]); w.w = cvt_pk_bf16(acc[1][vt][2], acc[1][vt][3]);
;                 __builtin_nontemporal_store(w, (u32x4*)(cs + (size_t)((vs * 4 + vt) * 8 + wid) * 512 + (fr * 4 + fq) * 8)); }
;             if (vs == 0) { if (fr == 0) { float* np = (float*)(p.ws + OFF_NST) + (size_t)(sid * 16 + ci) * 256 + wid * 32 + fq * 8; *(f32x4*)np = nacc[0]; *(f32x4*)(np + 4) = nacc[1]; }
;                 if (tid == 0) ((float*)(p.ws + OFF_MST))[sid * 16 + ci] = mprevA[st]; }
;         }
;         if (st == 17) break;
;         const LAS float* e_s = eA + st * 128; const float decay = decayA[st];
; #pragma unroll
;         for (int rep = 0; rep < 2; ++rep) { const int it = tid + rep * 512; const int v = (it >> 8) * 16 + ((it >> 2) & 15), sg = ((it >> 6) & 3) * 32 + (it & 3) * 8;
;             const u32x4 raw = vr[rep];
;             u32x4 w; w.x = cvt_pk_bf16(bf_lo(raw.x) * e_s[sg], bf_hi(raw.x) * e_s[sg + 1]); w.y = cvt_pk_bf16(bf_lo(raw.y) * e_s[sg + 2], bf_hi(raw.y) * e_s[sg + 3]);
;             w.z = cvt_pk_bf16(bf_lo(raw.z) * e_s[sg + 4], bf_hi(raw.z) * e_s[sg + 5]); w.w = cvt_pk_bf16(bf_lo(raw.w) * e_s[sg + 6], bf_hi(raw.w) * e_s[sg + 7]);
;             *(LAS u32x4*)(Ve + v * 136 + sg) = w; }
; #pragma unroll
.Lgb2_done:
	s_or_b64 exec, exec, s[12:13]
	s_waitcnt lgkmcnt(0)
	s_barrier
	global_load_dwordx4 v[10:13], v[0:1], off
	v_add_u32_e32 v6, 0x200, v4
	v_ashrrev_i32_e32 v7, 31, v6
	v_and_b32_e32 v100, 15, v4
	v_lshrrev_b32_e32 v0, 2, v4
	v_bfe_u32 v48, v4, 4, 2
	v_lshlrev_b32_e32 v1, 4, v4
	v_lshlrev_b64 v[84:85], 4, v[6:7]
	v_and_or_b32 v3, v0, 16, v100
	v_and_or_b32 v5, v1, 48, v48
	v_lshl_add_u64 v[0:1], s[6:7], 0, v[84:85]
	global_load_dwordx4 v[14:17], v[0:1], off
	v_mov_b32_e32 v83, 0
	v_lshlrev_b32_e32 v0, 1, v3
	v_lshlrev_b32_e32 v82, 4, v5
	v_lshlrev_b32_e32 v9, 3, v4
	v_ashrrev_i32_e32 v2, 7, v4
	v_and_b32_e32 v5, 56, v0
	v_lshl_add_u64 v[18:19], s[0:1], 0, v[82:83]
	v_lshrrev_b32_e32 v57, 1, v4
	s_movk_i32 s1, 0x60
	v_and_b32_e32 v9, 24, v9
	v_add_u32_e32 v0, v5, v2
	v_and_b32_e32 v50, 60, v8
	v_ashrrev_i32_e32 v8, 7, v6
	v_and_or_b32 v52, v57, s1, v9
	v_ashrrev_i32_e32 v1, 31, v0
	v_lshl_add_u32 v9, v52, 2, 0
	v_add_u32_e32 v8, v5, v8
	v_lshlrev_b64 v[86:87], 10, v[0:1]
	v_add_u32_e32 v91, 0x15400, v9
	v_ashrrev_i32_e32 v9, 31, v8
	v_lshl_add_u64 v[34:35], v[18:19], 0, v[86:87]
	v_lshlrev_b64 v[88:89], 10, v[8:9]
	global_load_dwordx4 v[0:3], v[34:35], off offset:192
	v_lshl_add_u64 v[8:9], v[18:19], 0, v[88:89]
	global_load_dwordx4 v[18:21], v[34:35], off offset:64
	global_load_dwordx4 v[22:25], v[34:35], off offset:128
	global_load_dwordx4 v[26:29], v[8:9], off
	global_load_dwordx4 v[30:33], v[8:9], off offset:64
	s_lshl_b32 s29, s29, 2
	global_load_dwordx4 v[34:37], v[34:35], off
	s_and_b32 s38, s29, 0x1f0
	s_cmp_eq_u32 s34, 0
	s_cselect_b64 s[6:7], -1, 0
	s_add_i32 s1, 0, 0x17900
	v_mov_b32_e32 v5, s1
	ds_read_b32 v53, v5
	ds_read_b64 v[46:47], v91
	global_load_dwordx4 v[38:41], v[8:9], off offset:128
	global_load_dwordx4 v[42:45], v[8:9], off offset:192
	v_lshrrev_b32_e32 v7, 4, v4
	v_bfe_u32 v49, v4, 2, 4
	s_mov_b32 s9, 0xffffff0
	v_and_b32_e32 v51, 64, v4
	s_movk_i32 s0, 0x110
	v_and_or_b32 v7, v7, s9, v49
	s_add_i32 s1, 0, 0x11000
	v_mul_lo_u32 v7, v7, s0
	v_lshlrev_b32_e32 v111, 1, v4
	v_lshlrev_b32_e32 v90, 5, v56
	v_and_b32_e32 v112, 3, v4
	v_and_b32_e32 v105, 48, v4
	v_add_u32_e32 v113, s1, v105
	v_lshrrev_b32_e32 v4, 5, v4
	s_mov_b32 s39, 0xffff0000
	s_xor_b32 s8, s8, 1
	v_readlane_b32 s16, v254, 31
	v_readlane_b32 s17, v254, 32
	v_lshl_add_u64 v[102:103], s[30:31], 0, v[82:83]
	s_mov_b32 s40, 0
	s_waitcnt vmcnt(9)
	v_and_b32_e32 v8, 0xffff0000, v10
	v_lshlrev_b32_e32 v5, 16, v10
	s_waitcnt lgkmcnt(0)
	v_mul_f32_e32 v8, v47, v8
	v_mul_f32_e32 v5, v46, v5
	v_cvt_pk_bf16_f32 v8, v5, v8
	ds_read_b64 v[46:47], v91 offset:8
	v_lshlrev_b32_e32 v9, 16, v11
	v_and_b32_e32 v10, 0xffff0000, v11
	v_lshlrev_b32_e32 v5, 1, v51
	v_lshl_add_u32 v51, v52, 1, s1
	s_waitcnt lgkmcnt(0)
	v_mul_f32_e32 v9, v46, v9
	v_mul_f32_e32 v10, v47, v10
	v_cvt_pk_bf16_f32 v9, v9, v10
	ds_read_b64 v[10:11], v91 offset:16
	v_lshlrev_b32_e32 v46, 16, v12
	v_and_b32_e32 v12, 0xffff0000, v12
	v_add_u32_e32 v106, v51, v7
	v_lshlrev_b32_e32 v7, 16, v13
	s_waitcnt lgkmcnt(0)
	v_mul_f32_e32 v10, v10, v46
	v_mul_f32_e32 v11, v11, v12
	v_cvt_pk_bf16_f32 v10, v10, v11
	ds_read_b64 v[46:47], v91 offset:24
	v_and_b32_e32 v11, 0xffff0000, v13
	v_and_b32_e32 v12, 24, v111
	s_mov_b32 s1, 0x1fffffc
	v_and_or_b32 v4, v4, s1, v48
	s_waitcnt lgkmcnt(0)
	v_mul_f32_e32 v11, v47, v11
	v_mul_f32_e32 v7, v46, v7
	v_cvt_pk_bf16_f32 v11, v7, v11
	ds_write_b128 v106, v[8:11]
	ds_read_b64 v[8:9], v91
	s_waitcnt vmcnt(8)
	v_lshlrev_b32_e32 v10, 16, v14
	v_and_b32_e32 v11, 0xffff0000, v14
	v_lshlrev_b32_e32 v7, 1, v50
	v_add3_u32 v7, 0, v5, v7
	s_waitcnt lgkmcnt(0)
	v_mul_f32_e32 v8, v8, v10
	v_mul_f32_e32 v9, v9, v11
	v_cvt_pk_bf16_f32 v8, v8, v9
	ds_read_b64 v[10:11], v91 offset:8
	v_and_b32_e32 v9, 0xffff0000, v15
	v_lshlrev_b32_e32 v5, 16, v15
	v_or3_b32 v14, v112, v12, v90
	v_and_b32_e32 v12, 0xffff0000, v16
	s_waitcnt lgkmcnt(0)
	v_mul_f32_e32 v9, v11, v9
	v_mul_f32_e32 v5, v10, v5
	v_cvt_pk_bf16_f32 v9, v5, v9
	ds_read_b64 v[10:11], v91 offset:16
	v_lshlrev_b32_e32 v5, 16, v16
	v_add_u32_e32 v46, 0, v105
	s_waitcnt lgkmcnt(0)
	v_mul_f32_e32 v5, v10, v5
	v_mul_f32_e32 v10, v11, v12
	v_cvt_pk_bf16_f32 v10, v5, v10
	ds_read_b64 v[12:13], v91 offset:24
	v_lshrrev_b32_e32 v5, 4, v6
	v_and_or_b32 v5, v5, s9, v49
	v_lshlrev_b32_e32 v11, 16, v17
	v_mul_lo_u32 v5, v5, s0
	s_movk_i32 s9, 0x880
	s_waitcnt lgkmcnt(0)
	v_mul_f32_e32 v11, v12, v11
	v_and_b32_e32 v12, 0xffff0000, v17
	v_add_u32_e32 v107, v51, v5
	v_mul_lo_u32 v4, v4, s9
	v_mul_f32_e32 v12, v13, v12
	v_cvt_pk_bf16_f32 v11, v11, v12
	ds_write_b128 v107, v[8:11]
	v_add_u32_e32 v108, v7, v4
	s_waitcnt vmcnt(2)
	v_and_b32_e32 v4, 0xffff, v34
	v_and_b32_e32 v5, 0xffff, v22
	v_lshrrev_b32_e32 v8, 16, v34
	v_lshrrev_b32_e32 v9, 16, v22
	v_lshl_or_b32 v4, v18, 16, v4
	v_lshl_or_b32 v5, v0, 16, v5
	v_and_or_b32 v8, v18, s39, v8
	v_and_or_b32 v9, v0, s39, v9
	v_and_b32_e32 v0, 0xffff, v35
	ds_write2_b64 v108, v[4:5], v[8:9] offset1:34
	v_lshl_or_b32 v4, v19, 16, v0
	v_and_b32_e32 v0, 0xffff, v23
	v_lshl_or_b32 v5, v1, 16, v0
	v_lshrrev_b32_e32 v0, 16, v35
	v_lshrrev_b32_e32 v8, 16, v23
	v_and_or_b32 v0, v19, s39, v0
	v_and_or_b32 v1, v1, s39, v8
	ds_write2_b64 v108, v[4:5], v[0:1] offset0:68 offset1:102
	v_and_b32_e32 v0, 0xffff, v36
	v_and_b32_e32 v1, 0xffff, v24
	v_lshrrev_b32_e32 v4, 16, v36
	v_lshrrev_b32_e32 v5, 16, v24
	v_lshl_or_b32 v0, v20, 16, v0
	v_lshl_or_b32 v1, v2, 16, v1
	v_and_or_b32 v4, v20, s39, v4
	v_and_or_b32 v5, v2, s39, v5
	ds_write2_b64 v108, v[0:1], v[4:5] offset0:136 offset1:170
	v_and_b32_e32 v0, 0xffff, v37
	v_and_b32_e32 v1, 0xffff, v25
	v_lshrrev_b32_e32 v2, 16, v37
	v_lshrrev_b32_e32 v4, 16, v25
	v_lshl_or_b32 v0, v21, 16, v0
	v_lshl_or_b32 v1, v3, 16, v1
	v_and_or_b32 v2, v21, s39, v2
	v_and_or_b32 v3, v3, s39, v4
	ds_write2_b64 v108, v[0:1], v[2:3] offset0:204 offset1:238
	v_lshrrev_b32_e32 v0, 5, v6
	v_and_or_b32 v0, v0, s1, v48
	v_mul_lo_u32 v0, v0, s9
	v_add_u32_e32 v109, v7, v0
	v_and_b32_e32 v0, 0xffff, v26
	s_waitcnt vmcnt(1)
; __device__ void passA(const Params& p, LAS unsigned char* lds, int wg) {
;     ...
;         for (int rep = 0; rep < 2; ++rep) { const int it = tid + rep * 512; const int sq = (it & 15) | (((it >> 6) & 1) << 4), ko = ((it >> 4) & 3) | ((it >> 7) << 2);
;             const u32x4 r0 = kr[rep][0], r1 = kr[rep][1], r2 = kr[rep][2], r3 = kr[rep][3];
;             LAS bf16_t* dst = Kt + (ko * 8) * 136 + sq * 4;
;     ...
;             TRW(0, r0.x, r1.x, r2.x, r3.x, 0) TRW(1, r0.x, r1.x, r2.x, r3.x, 1) TRW(2, r0.y, r1.y, r2.y, r3.y, 0) TRW(3, r0.y, r1.y, r2.y, r3.y, 1)
;             TRW(4, r0.z, r1.z, r2.z, r3.z, 0) TRW(5, r0.z, r1.z, r2.z, r3.z, 1) TRW(6, r0.w, r1.w, r2.w, r3.w, 0) TRW(7, r0.w, r1.w, r2.w, r3.w, 1)
;     ...
;         }
;         __syncthreads();
;         if (st + 1 < 17) {
;             bool ic2; int ci2; const bf16_t* Kb2; const bf16_t* Vb2; passA_chunk(p, st + 1, b, h, dir, vs, ic2, ci2, Kb2, Vb2);
; #pragma unroll
;             for (int rep = 0; rep < 2; ++rep) { const int it = tid + rep * 512;
;                 vr[rep] = *(const u32x4*)(Vb2 + (size_t)it * 8);
;                 const int sq = (it & 15) | (((it >> 6) & 1) << 4), ko = ((it >> 4) & 3) | ((it >> 7) << 2); const bf16_t* src = Kb2 + (size_t)((sq >> 2) * 8 + (ko >> 2)) * 512 + ((sq & 3) * 16 + (ko & 3)) * 8;
;                 kr[rep][0] = *(const u32x4*)src; kr[rep][1] = *(const u32x4*)(src + 32); kr[rep][2] = *(const u32x4*)(src + 64); kr[rep][3] = *(const u32x4*)(src + 96); } }
; #pragma unroll
;         for (int a = 0; a < 2; ++a) { nacc[a] *= decay;
; #pragma unroll
;             for (int v = 0; v < 4; ++v) acc[a][v] *= decay; }
; #pragma unroll
;         for (int ks = 0; ks < 4; ++ks) { bf16x8 kf[2], vf[4];
; #pragma unroll
;             for (int kt = 0; kt < 2; ++kt) kf[kt] = *(const LAS bf16x8*)(Kt + (wid * 32 + 8 * (fr >> 2) + 4 * kt + (fr & 3)) * 136 + ks * 32 + fq * 8);
; #pragma unroll
;             for (int vt = 0; vt < 4; ++vt) vf[vt] = *(const LAS bf16x8*)(Ve + (vt * 16 + fr) * 136 + ks * 32 + fq * 8);
;             bf16x8 ef = *(const LAS bf16x8*)(eB + st * 128 + ks * 32 + fq * 8);
;             if (fr != 0) ef = (bf16x8){0, 0, 0, 0, 0, 0, 0, 0};
; #pragma unroll
;             for (int kt = 0; kt < 2; ++kt) {
; #pragma unroll
;                 for (int vt = 0; vt < 4; ++vt) acc[kt][vt] = __builtin_amdgcn_mfma_f32_16x16x32_bf16(kf[kt], vf[vt], acc[kt][vt], 0, 0, 0);
	v_and_b32_e32 v1, 0xffff, v38
	v_lshrrev_b32_e32 v2, 16, v26
	v_lshrrev_b32_e32 v3, 16, v38
	v_lshl_or_b32 v0, v30, 16, v0
	s_waitcnt vmcnt(0)
	v_lshl_or_b32 v1, v42, 16, v1
	v_and_or_b32 v2, v30, s39, v2
	v_and_or_b32 v3, v42, s39, v3
	ds_write2_b64 v109, v[0:1], v[2:3] offset1:34
	v_and_b32_e32 v0, 0xffff, v27
	v_and_b32_e32 v1, 0xffff, v39
	v_lshrrev_b32_e32 v2, 16, v27
	v_lshrrev_b32_e32 v3, 16, v39
	v_lshl_or_b32 v0, v31, 16, v0
	v_lshl_or_b32 v1, v43, 16, v1
	v_and_or_b32 v2, v31, s39, v2
	v_and_or_b32 v3, v43, s39, v3
	ds_write2_b64 v109, v[0:1], v[2:3] offset0:68 offset1:102
	v_and_b32_e32 v0, 0xffff, v28
	v_and_b32_e32 v1, 0xffff, v40
	v_lshrrev_b32_e32 v2, 16, v28
	v_lshrrev_b32_e32 v3, 16, v40
	v_lshl_or_b32 v0, v32, 16, v0
	v_lshl_or_b32 v1, v44, 16, v1
	v_and_or_b32 v2, v32, s39, v2
	v_and_or_b32 v3, v44, s39, v3
	ds_write2_b64 v109, v[0:1], v[2:3] offset0:136 offset1:170
	v_and_b32_e32 v0, 0xffff, v29
	v_and_b32_e32 v1, 0xffff, v41
	v_lshrrev_b32_e32 v2, 16, v29
	v_lshrrev_b32_e32 v3, 16, v41
	v_lshl_or_b32 v0, v33, 16, v0
	v_lshl_or_b32 v1, v45, 16, v1
	v_and_or_b32 v2, v33, s39, v2
	v_and_or_b32 v3, v45, s39, v3
	ds_write2_b64 v109, v[0:1], v[2:3] offset0:204 offset1:238
	v_mul_lo_u32 v1, v14, s0
	v_add_u32_e32 v110, v46, v1
	s_waitcnt lgkmcnt(0)
	s_barrier
	ds_read_b128 v[4:7], v110
	v_mad_u32_u24 v29, v100, s0, v113
	ds_read_b128 v[8:11], v29
	v_add_u32_e32 v30, 0x17a80, v46
	v_mul_f32_e32 v0, 0, v53
	ds_read_b128 v[12:15], v29 offset:4352
	ds_read_b128 v[16:19], v110 offset:64
	ds_read_b128 v[20:23], v29 offset:64
	ds_read_b128 v[32:35], v29 offset:8704
	ds_read_b128 v[36:39], v29 offset:4416
	ds_read_b128 v[44:47], v29 offset:13056
	ds_read_b128 v[48:51], v30
	ds_read_b128 v[52:55], v29 offset:8768
	ds_read_b128 v[62:65], v30 offset:64
	ds_read_b128 v[66:69], v29 offset:13120
	ds_read_b128 v[74:77], v110 offset:1088
	ds_read_b128 v[92:95], v110 offset:1152
	v_mov_b32_e32 v1, v0
	v_mov_b32_e32 v2, v0
	v_mov_b32_e32 v3, v0
	s_lshl_b32 s9, s8, 2
	s_or_b32 s12, s9, s25
	s_waitcnt lgkmcnt(12)
	v_mfma_f32_16x16x32_bf16 v[24:27], v[4:7], v[8:11], v[0:3]
	v_cmp_eq_u32_e64 s[0:1], 0, v100
	s_ashr_i32 s13, s12, 31
	s_lshl_b64 s[12:13], s[12:13], 16
	s_waitcnt lgkmcnt(1)
	v_mfma_f32_16x16x32_bf16 v[8:11], v[74:77], v[8:11], v[0:3]
	v_cndmask_b32_e64 v51, 0, v51, s[0:1]
	v_cndmask_b32_e64 v50, 0, v50, s[0:1]
	v_cndmask_b32_e64 v49, 0, v49, s[0:1]
	v_mfma_f32_16x16x32_bf16 v[40:43], v[4:7], v[12:15], v[0:3]
	v_cndmask_b32_e64 v48, 0, v48, s[0:1]
	s_add_u32 s12, s11, s12
	s_addc_u32 s13, s14, s13
	v_mfma_f32_16x16x32_bf16 v[12:15], v[74:77], v[12:15], v[0:3]
	s_ashr_i32 s9, s8, 31
	s_lshl_b64 s[8:9], s[8:9], 18
	s_add_u32 s3, s3, s8
	v_mfma_f32_16x16x32_bf16 v[24:27], v[16:19], v[20:23], v[24:27]
	s_addc_u32 s9, s27, s9
	s_add_u32 s8, s3, s10
	s_addc_u32 s9, s9, 0
	s_waitcnt lgkmcnt(0)
	v_mfma_f32_16x16x32_bf16 v[8:11], v[92:95], v[20:23], v[8:11]
	ds_read_b128 v[20:23], v110 offset:128
	v_lshl_add_u64 v[78:79], s[8:9], 0, v[84:85]
	s_add_i32 s3, 0, 0x17904
	v_mfma_f32_16x16x32_bf16 v[58:61], v[4:7], v[32:35], v[0:3]
	s_cmp_eq_u32 s28, 0
	s_mov_b32 s27, 2
	s_mov_b32 s28, 14
	v_mfma_f32_16x16x32_bf16 v[70:73], v[4:7], v[44:47], v[0:3]
	v_mfma_f32_16x16x32_bf16 v[4:7], v[4:7], v[48:51], v[0:3]
	v_mfma_f32_16x16x32_bf16 v[32:35], v[74:77], v[32:35], v[0:3]
	v_mfma_f32_16x16x32_bf16 v[44:47], v[74:77], v[44:47], v[0:3]
	v_mfma_f32_16x16x32_bf16 v[0:3], v[74:77], v[48:51], v[0:3]
	v_mfma_f32_16x16x32_bf16 v[40:43], v[16:19], v[36:39], v[40:43]
	v_mfma_f32_16x16x32_bf16 v[12:15], v[92:95], v[36:39], v[12:15]
	ds_read_b128 v[36:39], v29 offset:128
	v_mfma_f32_16x16x32_bf16 v[48:51], v[16:19], v[52:55], v[58:61]
	s_nop 2
	v_cndmask_b32_e64 v61, 0, v65, s[0:1]
	v_cndmask_b32_e64 v60, 0, v64, s[0:1]
	v_cndmask_b32_e64 v59, 0, v63, s[0:1]
	v_cndmask_b32_e64 v58, 0, v62, s[0:1]
	v_mfma_f32_16x16x32_bf16 v[70:73], v[16:19], v[66:69], v[70:73]
	s_nop 0
	v_mfma_f32_16x16x32_bf16 v[4:7], v[16:19], v[58:61], v[4:7]
	v_mfma_f32_16x16x32_bf16 v[16:19], v[92:95], v[52:55], v[32:35]
	v_mfma_f32_16x16x32_bf16 v[32:35], v[92:95], v[66:69], v[44:47]
	v_mfma_f32_16x16x32_bf16 v[0:3], v[92:95], v[58:61], v[0:3]
	s_nop 1
	ds_read_b128 v[44:47], v29 offset:4480
	ds_read_b128 v[52:55], v110 offset:192
	ds_read_b128 v[58:61], v29 offset:192
	ds_read_b128 v[62:65], v110 offset:1216
	ds_read_b128 v[66:69], v29 offset:8832
	ds_read_b128 v[74:77], v29 offset:4544
	ds_read_b128 v[92:95], v30 offset:128
	ds_read_b128 v[96:99], v29 offset:13184
	ds_read_b128 v[114:117], v29 offset:8896
	s_waitcnt lgkmcnt(9)
	v_mfma_f32_16x16x32_bf16 v[24:27], v[20:23], v[36:39], v[24:27]
	ds_read_b128 v[118:121], v30 offset:192
	ds_read_b128 v[122:125], v29 offset:13248
	s_waitcnt lgkmcnt(4)
	v_cndmask_b32_e64 v95, 0, v95, s[0:1]
	v_mfma_f32_16x16x32_bf16 v[8:11], v[62:65], v[36:39], v[8:11]
	v_lshl_add_u64 v[36:37], s[8:9], 0, v[80:81]
	global_load_dwordx4 v[36:39], v[36:37], off
	v_cndmask_b32_e64 v94, 0, v94, s[0:1]
	v_mfma_f32_16x16x32_bf16 v[40:43], v[20:23], v[44:47], v[40:43]
	v_cndmask_b32_e64 v93, 0, v93, s[0:1]
	v_cndmask_b32_e64 v92, 0, v92, s[0:1]
	s_cselect_b64 s[8:9], -1, 0
	v_mfma_f32_16x16x32_bf16 v[48:51], v[20:23], v[66:69], v[48:51]
	v_mfma_f32_16x16x32_bf16 v[12:15], v[62:65], v[44:47], v[12:15]
	v_mfma_f32_16x16x32_bf16 v[44:47], v[62:65], v[66:69], v[16:19]
	global_load_dwordx4 v[66:69], v[78:79], off
	s_waitcnt vmcnt(0)
	v_lshlrev_b32_e32 v31, 16, v68
	v_lshl_add_u64 v[16:17], s[12:13], 0, v[82:83]
	v_lshl_add_u64 v[18:19], v[16:17], 0, v[86:87]
	s_waitcnt lgkmcnt(3)
	v_mfma_f32_16x16x32_bf16 v[70:73], v[20:23], v[96:99], v[70:73]
	global_load_dwordx4 v[126:129], v[18:19], off
	s_and_b64 s[12:13], s[8:9], exec
	s_cselect_b32 s11, 0, 15
	v_mfma_f32_16x16x32_bf16 v[32:35], v[62:65], v[96:99], v[32:35]
	global_load_dwordx4 v[96:99], v[18:19], off offset:192
	v_mfma_f32_16x16x32_bf16 v[4:7], v[20:23], v[92:95], v[4:7]
	ds_read_b128 v[20:23], v110 offset:1280
	v_mfma_f32_16x16x32_bf16 v[62:65], v[62:65], v[92:95], v[0:3]
	global_load_dwordx4 v[92:95], v[18:19], off offset:64
	global_load_dwordx4 v[130:133], v[18:19], off offset:128
	s_nop 0
	v_lshl_add_u64 v[0:1], v[16:17], 0, v[88:89]
	global_load_dwordx4 v[138:141], v[0:1], off
	global_load_dwordx4 v[142:145], v[0:1], off offset:64
	global_load_dwordx4 v[146:149], v[0:1], off offset:128
	global_load_dwordx4 v[150:153], v[0:1], off offset:192
	s_waitcnt lgkmcnt(0)
	s_barrier
; #define LAS __attribute__((address_space(3)))
; __device__ void passA(const Params& p, LAS unsigned char* lds, int wg) {
;     ...
;         const LAS float* e_s = eA + st * 128; const float decay = decayA[st];
; #pragma unroll
;         for (int rep = 0; rep < 2; ++rep) { const int it = tid + rep * 512; const int v = (it >> 8) * 16 + ((it >> 2) & 15), sg = ((it >> 6) & 3) * 32 + (it & 3) * 8;
;             const u32x4 raw = vr[rep];
;             u32x4 w; w.x = cvt_pk_bf16(bf_lo(raw.x) * e_s[sg], bf_hi(raw.x) * e_s[sg + 1]); w.y = cvt_pk_bf16(bf_lo(raw.y) * e_s[sg + 2], bf_hi(raw.y) * e_s[sg + 3]);
;             w.z = cvt_pk_bf16(bf_lo(raw.z) * e_s[sg + 4], bf_hi(raw.z) * e_s[sg + 5]); w.w = cvt_pk_bf16(bf_lo(raw.w) * e_s[sg + 6], bf_hi(raw.w) * e_s[sg + 7]);
;             *(LAS u32x4*)(Ve + v * 136 + sg) = w; }
; #pragma unroll
;         for (int rep = 0; rep < 2; ++rep) { const int it = tid + rep * 512; const int sq = (it & 15) | (((it >> 6) & 1) << 4), ko = ((it >> 4) & 3) | ((it >> 7) << 2);
;             const u32x4 r0 = kr[rep][0], r1 = kr[rep][1], r2 = kr[rep][2], r3 = kr[rep][3];
;             LAS bf16_t* dst = Kt + (ko * 8) * 136 + sq * 4;
;     ...
;             TRW(0, r0.x, r1.x, r2.x, r3.x, 0) TRW(1, r0.x, r1.x, r2.x, r3.x, 1) TRW(2, r0.y, r1.y, r2.y, r3.y, 0) TRW(3, r0.y, r1.y, r2.y, r3.y, 1)
;             TRW(4, r0.z, r1.z, r2.z, r3.z, 0) TRW(5, r0.z, r1.z, r2.z, r3.z, 1) TRW(6, r0.w, r1.w, r2.w, r3.w, 0) TRW(7, r0.w, r1.w, r2.w, r3.w, 1)
;     ...
;         }
;         __syncthreads();
;         if (st + 1 < 17) {
;             bool ic2; int ci2; const bf16_t* Kb2; const bf16_t* Vb2; passA_chunk(p, st + 1, b, h, dir, vs, ic2, ci2, Kb2, Vb2);
; #pragma unroll
;             for (int rep = 0; rep < 2; ++rep) { const int it = tid + rep * 512;
;                 vr[rep] = *(const u32x4*)(Vb2 + (size_t)it * 8);
;                 const int sq = (it & 15) | (((it >> 6) & 1) << 4), ko = ((it >> 4) & 3) | ((it >> 7) << 2); const bf16_t* src = Kb2 + (size_t)((sq >> 2) * 8 + (ko >> 2)) * 512 + ((sq & 3) * 16 + (ko & 3)) * 8;
;                 kr[rep][0] = *(const u32x4*)src; kr[rep][1] = *(const u32x4*)(src + 32); kr[rep][2] = *(const u32x4*)(src + 64); kr[rep][3] = *(const u32x4*)(src + 96); } }
; #pragma unroll
;         for (int a = 0; a < 2; ++a) { nacc[a] *= decay;
; #pragma unroll
;             for (int v = 0; v < 4; ++v) acc[a][v] *= decay; }
	ds_read_b64 v[0:1], v91 offset:512
	v_mov_b32_e32 v2, s3
	ds_read_b32 v28, v2
	v_lshlrev_b32_e32 v2, 16, v36
	v_mfma_f32_16x16x32_bf16 v[16:19], v[52:55], v[114:117], v[48:51]
	s_waitcnt lgkmcnt(1)
	v_mul_f32_e32 v0, v0, v2
	v_and_b32_e32 v2, 0xffff0000, v36
	v_mul_f32_e32 v1, v1, v2
	v_cvt_pk_bf16_f32 v36, v0, v1
	ds_read_b64 v[0:1], v91 offset:520
	v_lshlrev_b32_e32 v2, 16, v37
	v_cndmask_b32_e64 v51, 0, v121, s[0:1]
	v_cndmask_b32_e64 v50, 0, v120, s[0:1]
	v_cndmask_b32_e64 v49, 0, v119, s[0:1]
	s_waitcnt lgkmcnt(0)
	v_mul_f32_e32 v0, v0, v2
	v_and_b32_e32 v2, 0xffff0000, v37
	v_mul_f32_e32 v1, v1, v2
	v_cvt_pk_bf16_f32 v37, v0, v1
	ds_read_b64 v[0:1], v91 offset:528
	v_lshlrev_b32_e32 v2, 16, v38
	v_cndmask_b32_e64 v48, 0, v118, s[0:1]
	v_mfma_f32_16x16x32_bf16 v[134:137], v[52:55], v[58:61], v[24:27]
	v_mul_f32_e64 v18, v18, v28
	v_mul_f32_e64 v19, v19, v28
	s_waitcnt lgkmcnt(0)
	v_mul_f32_e32 v0, v0, v2
	v_and_b32_e32 v2, 0xffff0000, v38
	v_mfma_f32_16x16x32_bf16 v[40:43], v[52:55], v[74:77], v[40:43]
	v_mul_f32_e32 v1, v1, v2
	v_cvt_pk_bf16_f32 v38, v0, v1
	v_pk_mul_f32 v[16:17], v[16:17], v[28:29] op_sel_hi:[1,0]
	v_mfma_f32_16x16x32_bf16 v[24:27], v[52:55], v[122:125], v[70:73]
	s_lshl_b32 s3, s46, 4
	s_nop 3
	v_pk_mul_f32 v[42:43], v[42:43], v[28:29] op_sel_hi:[1,0]
	v_pk_mul_f32 v[40:41], v[40:41], v[28:29] op_sel_hi:[1,0]
	v_mfma_f32_16x16x32_bf16 v[52:55], v[52:55], v[48:51], v[4:7]
	s_or_b32 s12, s11, s3
	v_pk_mul_f32 v[26:27], v[26:27], v[28:29] op_sel_hi:[1,0]
	v_pk_mul_f32 v[24:25], v[24:25], v[28:29] op_sel_hi:[1,0]
	ds_read_b64 v[4:5], v91 offset:536
	v_lshlrev_b32_e32 v6, 16, v39
	v_mfma_f32_16x16x32_bf16 v[0:3], v[20:23], v[58:61], v[8:11]
	s_lshl_b32 s11, s12, 2
	s_or_b32 s14, s11, s25
	s_waitcnt lgkmcnt(0)
	v_mul_f32_e32 v4, v4, v6
	v_and_b32_e32 v6, 0xffff0000, v39
	v_mul_f32_e32 v5, v5, v6
	v_cvt_pk_bf16_f32 v39, v4, v5
	ds_write_b128 v106, v[36:39]
	ds_read_b64 v[8:9], v91 offset:512
	v_lshlrev_b32_e32 v10, 16, v66
	v_mfma_f32_16x16x32_bf16 v[4:7], v[20:23], v[74:77], v[12:15]
	v_mul_f32_e64 v2, v2, v28
	v_mul_f32_e64 v3, v3, v28
	v_pk_mul_f32 v[0:1], v[0:1], v[28:29] op_sel_hi:[1,0]
	s_waitcnt lgkmcnt(0)
	v_mul_f32_e32 v8, v8, v10
	v_and_b32_e32 v10, 0xffff0000, v66
	v_mul_f32_e32 v9, v9, v10
	v_cvt_pk_bf16_f32 v36, v8, v9
	ds_read_b64 v[12:13], v91 offset:520
	v_lshlrev_b32_e32 v14, 16, v67
	v_mfma_f32_16x16x32_bf16 v[8:11], v[20:23], v[114:117], v[44:47]
	v_mul_f32_e64 v6, v6, v28
	v_mul_f32_e64 v7, v7, v28
	v_pk_mul_f32 v[4:5], v[4:5], v[28:29] op_sel_hi:[1,0]
	s_waitcnt lgkmcnt(0)
	v_mul_f32_e32 v12, v12, v14
	v_and_b32_e32 v14, 0xffff0000, v67
	v_mul_f32_e32 v13, v13, v14
	v_cvt_pk_bf16_f32 v37, v12, v13
	ds_read_b64 v[38:39], v91 offset:528
	v_mfma_f32_16x16x32_bf16 v[12:15], v[20:23], v[122:125], v[32:35]
	v_mul_f32_e64 v10, v10, v28
	v_mul_f32_e64 v11, v11, v28
	v_pk_mul_f32 v[8:9], v[8:9], v[28:29] op_sel_hi:[1,0]
	s_ashr_i32 s15, s14, 31
	v_and_b32_e32 v32, 0xffff0000, v68
	s_waitcnt lgkmcnt(0)
	v_mul_f32_e32 v32, v39, v32
	v_mul_f32_e32 v31, v38, v31
	v_cvt_pk_bf16_f32 v38, v31, v32
	ds_read_b64 v[32:33], v91 offset:536
	v_lshlrev_b32_e32 v31, 16, v69
	v_mfma_f32_16x16x32_bf16 v[20:23], v[20:23], v[48:51], v[62:65]
	v_mul_f32_e64 v14, v14, v28
	v_mul_f32_e64 v15, v15, v28
	v_pk_mul_f32 v[12:13], v[12:13], v[28:29] op_sel_hi:[1,0]
	s_waitcnt lgkmcnt(0)
	v_mul_f32_e32 v31, v32, v31
	v_and_b32_e32 v32, 0xffff0000, v69
	v_mul_f32_e32 v32, v33, v32
	v_cvt_pk_bf16_f32 v39, v31, v32
	s_waitcnt vmcnt(7)
	v_and_b32_e32 v31, 0xffff, v126
	s_waitcnt vmcnt(5)
	v_lshl_or_b32 v32, v92, 16, v31
	s_waitcnt vmcnt(4)
	v_and_b32_e32 v31, 0xffff, v130
	v_lshl_or_b32 v33, v96, 16, v31
	v_lshrrev_b32_e32 v31, 16, v126
	v_and_or_b32 v34, v92, s39, v31
	v_lshrrev_b32_e32 v31, 16, v130
	v_and_or_b32 v35, v96, s39, v31
	v_and_b32_e32 v31, 0xffff, v127
	ds_write_b128 v107, v[36:39]
	ds_write2_b64 v108, v[32:33], v[34:35] offset1:34
	v_lshl_or_b32 v32, v93, 16, v31
	v_and_b32_e32 v31, 0xffff, v131
	v_lshl_or_b32 v33, v97, 16, v31
	v_lshrrev_b32_e32 v31, 16, v127
	v_and_or_b32 v34, v93, s39, v31
	v_lshrrev_b32_e32 v31, 16, v131
	v_and_or_b32 v35, v97, s39, v31
	v_and_b32_e32 v31, 0xffff, v128
	ds_write2_b64 v108, v[32:33], v[34:35] offset0:68 offset1:102
	v_lshl_or_b32 v32, v94, 16, v31
	v_and_b32_e32 v31, 0xffff, v132
	v_lshl_or_b32 v33, v98, 16, v31
	v_lshrrev_b32_e32 v31, 16, v128
	v_and_or_b32 v34, v94, s39, v31
	v_lshrrev_b32_e32 v31, 16, v132
	v_and_or_b32 v35, v98, s39, v31
	v_and_b32_e32 v31, 0xffff, v129
	ds_write2_b64 v108, v[32:33], v[34:35] offset0:136 offset1:170
	v_lshl_or_b32 v32, v95, 16, v31
	v_and_b32_e32 v31, 0xffff, v133
	v_lshl_or_b32 v33, v99, 16, v31
	v_lshrrev_b32_e32 v31, 16, v129
	v_and_or_b32 v34, v95, s39, v31
	v_lshrrev_b32_e32 v31, 16, v133
	v_and_or_b32 v35, v99, s39, v31
	s_waitcnt vmcnt(3)
	v_and_b32_e32 v31, 0xffff, v138
	ds_write2_b64 v108, v[32:33], v[34:35] offset0:204 offset1:238
	s_waitcnt vmcnt(2)
	v_lshl_or_b32 v32, v142, 16, v31
	s_waitcnt vmcnt(1)
	v_and_b32_e32 v31, 0xffff, v146
	s_waitcnt vmcnt(0)
	v_lshl_or_b32 v33, v150, 16, v31
	v_lshrrev_b32_e32 v31, 16, v138
	v_and_or_b32 v34, v142, s39, v31
	v_lshrrev_b32_e32 v31, 16, v146
	v_and_or_b32 v35, v150, s39, v31
	v_and_b32_e32 v31, 0xffff, v139
	ds_write2_b64 v109, v[32:33], v[34:35] offset1:34
	v_lshl_or_b32 v32, v143, 16, v31
	v_and_b32_e32 v31, 0xffff, v147
	v_lshl_or_b32 v33, v151, 16, v31
	v_lshrrev_b32_e32 v31, 16, v139
	v_and_or_b32 v34, v143, s39, v31
	v_lshrrev_b32_e32 v31, 16, v147
	v_and_or_b32 v35, v151, s39, v31
	v_and_b32_e32 v31, 0xffff, v140
	ds_write2_b64 v109, v[32:33], v[34:35] offset0:68 offset1:102
	v_lshl_or_b32 v32, v144, 16, v31
	v_and_b32_e32 v31, 0xffff, v148
	v_lshl_or_b32 v33, v152, 16, v31
	v_lshrrev_b32_e32 v31, 16, v140
	v_and_or_b32 v34, v144, s39, v31
	v_lshrrev_b32_e32 v31, 16, v148
	v_and_or_b32 v35, v152, s39, v31
	v_and_b32_e32 v31, 0xffff, v141
	ds_write2_b64 v109, v[32:33], v[34:35] offset0:136 offset1:170
	v_lshl_or_b32 v32, v145, 16, v31
	v_and_b32_e32 v31, 0xffff, v149
	v_lshl_or_b32 v33, v153, 16, v31
	v_lshrrev_b32_e32 v31, 16, v141
	v_and_or_b32 v34, v145, s39, v31
	v_lshrrev_b32_e32 v31, 16, v149
	v_and_or_b32 v35, v153, s39, v31
	ds_write2_b64 v109, v[32:33], v[34:35] offset0:204 offset1:238
	s_waitcnt lgkmcnt(0)
	s_barrier
; #define LAS __attribute__((address_space(3)))
; __device__ void passA(const Params& p, LAS unsigned char* lds, int wg) {
;     ...
;         if (st + 1 < 17) {
;             bool ic2; int ci2; const bf16_t* Kb2; const bf16_t* Vb2; passA_chunk(p, st + 1, b, h, dir, vs, ic2, ci2, Kb2, Vb2);
; #pragma unroll
;             for (int rep = 0; rep < 2; ++rep) { const int it = tid + rep * 512;
;                 vr[rep] = *(const u32x4*)(Vb2 + (size_t)it * 8);
;                 const int sq = (it & 15) | (((it >> 6) & 1) << 4), ko = ((it >> 4) & 3) | ((it >> 7) << 2); const bf16_t* src = Kb2 + (size_t)((sq >> 2) * 8 + (ko >> 2)) * 512 + ((sq & 3) * 16 + (ko & 3)) * 8;
;                 kr[rep][0] = *(const u32x4*)src; kr[rep][1] = *(const u32x4*)(src + 32); kr[rep][2] = *(const u32x4*)(src + 64); kr[rep][3] = *(const u32x4*)(src + 96); } }
; #pragma unroll
;         for (int a = 0; a < 2; ++a) { nacc[a] *= decay;
; #pragma unroll
;             for (int v = 0; v < 4; ++v) acc[a][v] *= decay; }
; #pragma unroll
;         for (int ks = 0; ks < 4; ++ks) { bf16x8 kf[2], vf[4];
; #pragma unroll
;             for (int kt = 0; kt < 2; ++kt) kf[kt] = *(const LAS bf16x8*)(Kt + (wid * 32 + 8 * (fr >> 2) + 4 * kt + (fr & 3)) * 136 + ks * 32 + fq * 8);
; #pragma unroll
;             for (int vt = 0; vt < 4; ++vt) vf[vt] = *(const LAS bf16x8*)(Ve + (vt * 16 + fr) * 136 + ks * 32 + fq * 8);
;             bf16x8 ef = *(const LAS bf16x8*)(eB + st * 128 + ks * 32 + fq * 8);
;             if (fr != 0) ef = (bf16x8){0, 0, 0, 0, 0, 0, 0, 0};
; #pragma unroll
;             for (int kt = 0; kt < 2; ++kt) {
; #pragma unroll
;                 for (int vt = 0; vt < 4; ++vt) acc[kt][vt] = __builtin_amdgcn_mfma_f32_16x16x32_bf16(kf[kt], vf[vt], acc[kt][vt], 0, 0, 0);
;                 nacc[kt] = __builtin_amdgcn_mfma_f32_16x16x32_bf16(kf[kt], ef, nacc[kt], 0, 0, 0); } }
	ds_read_b128 v[44:47], v110
	ds_read_b128 v[48:51], v29
	v_pk_mul_f32 v[34:35], v[54:55], v[28:29] op_sel_hi:[1,0]
	v_pk_mul_f32 v[32:33], v[52:53], v[28:29] op_sel_hi:[1,0]
	ds_read_b128 v[52:55], v29 offset:4352
	ds_read_b128 v[58:61], v110 offset:64
	ds_read_b128 v[62:65], v29 offset:64
	ds_read_b128 v[66:69], v110 offset:1088
	ds_read_b128 v[70:73], v29 offset:8704
	ds_read_b128 v[74:77], v29 offset:4416
	ds_read_b128 v[92:95], v30 offset:256
	ds_read_b128 v[96:99], v29 offset:13056
	ds_read_b128 v[114:117], v29 offset:8768
	v_pk_mul_f32 v[38:39], v[136:137], v[28:29] op_sel_hi:[1,0]
	v_pk_mul_f32 v[36:37], v[134:135], v[28:29] op_sel_hi:[1,0]
	s_waitcnt lgkmcnt(2)
	v_cndmask_b32_e64 v95, 0, v95, s[0:1]
	v_cndmask_b32_e64 v94, 0, v94, s[0:1]
	v_cndmask_b32_e64 v93, 0, v93, s[0:1]
	v_cndmask_b32_e64 v92, 0, v92, s[0:1]
	v_mfma_f32_16x16x32_bf16 v[36:39], v[44:47], v[48:51], v[36:39]
	ds_read_b128 v[118:121], v30 offset:320
	ds_read_b128 v[122:125], v29 offset:13120
	v_pk_mul_f32 v[22:23], v[22:23], v[28:29] op_sel_hi:[1,0]
	v_mfma_f32_16x16x32_bf16 v[40:43], v[44:47], v[52:55], v[40:43]
	v_mul_f32_e64 v20, v20, v28
	v_mul_f32_e64 v21, v21, v28
	s_lshl_b64 s[14:15], s[14:15], 16
	s_add_u32 s14, s30, s14
	v_mfma_f32_16x16x32_bf16 v[16:19], v[44:47], v[70:73], v[16:19]
	s_addc_u32 s15, s31, s15
	s_ashr_i32 s13, s12, 31
	s_lshl_b64 s[12:13], s[12:13], 18
	s_waitcnt lgkmcnt(3)
	v_mfma_f32_16x16x32_bf16 v[24:27], v[44:47], v[96:99], v[24:27]
	s_add_u32 s11, s16, s12
	s_addc_u32 s13, s17, s13
	s_add_u32 s12, s11, s10
	v_mfma_f32_16x16x32_bf16 v[32:35], v[44:47], v[92:95], v[32:35]
	ds_read_b128 v[44:47], v110 offset:1152
	s_addc_u32 s13, s13, 0
	v_ashrrev_i32_e32 v91, 31, v90
	v_mfma_f32_16x16x32_bf16 v[4:7], v[66:69], v[52:55], v[4:7]
	ds_read_b128 v[52:55], v110 offset:128
	v_mfma_f32_16x16x32_bf16 v[0:3], v[66:69], v[48:51], v[0:3]
	s_waitcnt lgkmcnt(3)
	v_cndmask_b32_e64 v51, 0, v121, s[0:1]
	v_cndmask_b32_e64 v50, 0, v120, s[0:1]
	v_cndmask_b32_e64 v49, 0, v119, s[0:1]
	v_mfma_f32_16x16x32_bf16 v[8:11], v[66:69], v[70:73], v[8:11]
	v_cndmask_b32_e64 v48, 0, v118, s[0:1]
	v_mfma_f32_16x16x32_bf16 v[12:15], v[66:69], v[96:99], v[12:15]
	v_mfma_f32_16x16x32_bf16 v[20:23], v[66:69], v[92:95], v[20:23]
	v_mfma_f32_16x16x32_bf16 v[36:39], v[58:61], v[62:65], v[36:39]
	v_mfma_f32_16x16x32_bf16 v[40:43], v[58:61], v[74:77], v[40:43]
	v_mfma_f32_16x16x32_bf16 v[16:19], v[58:61], v[114:117], v[16:19]
	s_waitcnt lgkmcnt(2)
	v_mfma_f32_16x16x32_bf16 v[24:27], v[58:61], v[122:125], v[24:27]
	v_mfma_f32_16x16x32_bf16 v[32:35], v[58:61], v[48:51], v[32:35]
	ds_read_b128 v[58:61], v29 offset:128
	s_waitcnt lgkmcnt(2)
	v_mfma_f32_16x16x32_bf16 v[0:3], v[44:47], v[62:65], v[0:3]
	v_mfma_f32_16x16x32_bf16 v[4:7], v[44:47], v[74:77], v[4:7]
	v_mfma_f32_16x16x32_bf16 v[8:11], v[44:47], v[114:117], v[8:11]
	v_mfma_f32_16x16x32_bf16 v[12:15], v[44:47], v[122:125], v[12:15]
	v_mfma_f32_16x16x32_bf16 v[20:23], v[44:47], v[48:51], v[20:23]
	ds_read_b128 v[44:47], v29 offset:4480
	ds_read_b128 v[48:51], v110 offset:192
	ds_read_b128 v[92:95], v29 offset:192
	ds_read_b128 v[62:65], v110 offset:1216
	ds_read_b128 v[66:69], v29 offset:8832
	ds_read_b128 v[96:99], v29 offset:4544
	ds_read_b128 v[70:73], v30 offset:384
	ds_read_b128 v[74:77], v29 offset:13184
	ds_read_b128 v[114:117], v29 offset:8896
	ds_read_b128 v[118:121], v30 offset:448
	ds_read_b128 v[122:125], v29 offset:13248
	s_waitcnt lgkmcnt(11)
	v_mfma_f32_16x16x32_bf16 v[36:39], v[52:55], v[58:61], v[36:39]
	s_waitcnt lgkmcnt(4)
	v_cndmask_b32_e64 v31, 0, v73, s[0:1]
	v_cndmask_b32_e64 v30, 0, v72, s[0:1]
	v_cndmask_b32_e64 v29, 0, v71, s[0:1]
	v_cndmask_b32_e64 v28, 0, v70, s[0:1]
	v_mfma_f32_16x16x32_bf16 v[40:43], v[52:55], v[44:47], v[40:43]
	s_waitcnt lgkmcnt(1)
	v_cndmask_b32_e64 v121, 0, v121, s[0:1]
	v_cndmask_b32_e64 v120, 0, v120, s[0:1]
	v_cndmask_b32_e64 v119, 0, v119, s[0:1]
	v_mfma_f32_16x16x32_bf16 v[16:19], v[52:55], v[66:69], v[16:19]
	v_cndmask_b32_e64 v118, 0, v118, s[0:1]
	ds_read_b128 v[126:129], v110 offset:1280
	v_mfma_f32_16x16x32_bf16 v[24:27], v[52:55], v[74:77], v[24:27]
	v_mfma_f32_16x16x32_bf16 v[32:35], v[52:55], v[28:31], v[32:35]
	v_mfma_f32_16x16x32_bf16 v[138:141], v[62:65], v[28:31], v[20:23]
	v_lshl_add_u64 v[28:29], s[14:15], 0, v[82:83]
	s_mov_b64 s[14:15], 0x2000
	v_mfma_f32_16x16x32_bf16 v[52:55], v[62:65], v[58:61], v[0:3]
	v_lshl_add_u64 v[20:21], v[28:29], 0, v[86:87]
	v_lshl_add_u64 v[22:23], s[12:13], 0, v[84:85]
	v_mfma_f32_16x16x32_bf16 v[134:137], v[62:65], v[74:77], v[12:15]
	v_lshl_add_u64 v[0:1], s[12:13], 0, v[80:81]
	s_add_u32 s12, s70, 0xbc00000
	s_addc_u32 s13, s71, 0
	v_mfma_f32_16x16x32_bf16 v[72:75], v[48:51], v[92:95], v[36:39]
	s_cmp_lt_i32 s26, 32
	s_mov_b32 s26, 0xffff
	s_nop 0
	v_lshl_add_u64 v[36:37], v[28:29], 0, v[88:89]
	v_mfma_f32_16x16x32_bf16 v[58:61], v[62:65], v[44:47], v[4:7]
	v_mfma_f32_16x16x32_bf16 v[130:133], v[62:65], v[66:69], v[8:11]
	s_nop 2
	global_load_dwordx4 v[8:11], v[0:1], off
	s_nop 0
	global_load_dwordx4 v[0:3], v[20:21], off
	global_load_dwordx4 v[4:7], v[20:21], off offset:64
	global_load_dwordx4 v[12:15], v[20:21], off offset:128
	v_mfma_f32_16x16x32_bf16 v[68:71], v[48:51], v[96:99], v[40:43]
	v_mfma_f32_16x16x32_bf16 v[64:67], v[48:51], v[114:117], v[16:19]
	s_nop 2
	global_load_dwordx4 v[16:19], v[20:21], off offset:192
	s_nop 0
	global_load_dwordx4 v[20:23], v[22:23], off
	s_waitcnt lgkmcnt(1)
	v_mfma_f32_16x16x32_bf16 v[40:43], v[48:51], v[122:125], v[24:27]
	s_nop 2
	global_load_dwordx4 v[24:27], v[36:37], off
	global_load_dwordx4 v[28:31], v[36:37], off offset:64
	v_mfma_f32_16x16x32_bf16 v[76:79], v[48:51], v[118:121], v[32:35]
	s_nop 2
	global_load_dwordx4 v[32:35], v[36:37], off offset:128
	s_nop 0
	global_load_dwordx4 v[36:39], v[36:37], off offset:192
	s_waitcnt lgkmcnt(0)
	s_barrier
; __device__ void passA(const Params& p, LAS unsigned char* lds, int wg) {
;     ...
;             bf16_t* cs = cst_ptr(p, sid, ci);
; #pragma unroll
;             for (int vt = 0; vt < 4; ++vt) { u32x4 w; w.x = cvt_pk_bf16(acc[0][vt][0], acc[0][vt][1]); w.y = cvt_pk_bf16(acc[0][vt][2], acc[0][vt][3]);
;                 w.z = cvt_pk_bf16(acc[1][vt][0], acc[1][vt][1]); w.w = cvt_pk_bf16(acc[1][vt][2], acc[1][vt][3]);
;                 __builtin_nontemporal_store(w, (u32x4*)(cs + (size_t)((vs * 4 + vt) * 8 + wid) * 512 + (fr * 4 + fq) * 8)); }
;             if (vs == 0) { if (fr == 0) { float* np = (float*)(p.ws + OFF_NST) + (size_t)(sid * 16 + ci) * 256 + wid * 32 + fq * 8; *(f32x4*)np = nacc[0]; *(f32x4*)(np + 4) = nacc[1]; }
;                 if (tid == 0) ((float*)(p.ws + OFF_MST))[sid * 16 + ci] = mprevA[st]; }
;         }
;         if (st == 17) break;
;         const LAS float* e_s = eA + st * 128; const float decay = decayA[st];
; #pragma unroll
;         for (int rep = 0; rep < 2; ++rep) { const int it = tid + rep * 512; const int v = (it >> 8) * 16 + ((it >> 2) & 15), sg = ((it >> 6) & 3) * 32 + (it & 3) * 8;
;             const u32x4 raw = vr[rep];
;             u32x4 w; w.x = cvt_pk_bf16(bf_lo(raw.x) * e_s[sg], bf_hi(raw.x) * e_s[sg + 1]); w.y = cvt_pk_bf16(bf_lo(raw.y) * e_s[sg + 2], bf_hi(raw.y) * e_s[sg + 3]);
;             w.z = cvt_pk_bf16(bf_lo(raw.z) * e_s[sg + 4], bf_hi(raw.z) * e_s[sg + 5]); w.w = cvt_pk_bf16(bf_lo(raw.w) * e_s[sg + 6], bf_hi(raw.w) * e_s[sg + 7]);
;             *(LAS u32x4*)(Ve + v * 136 + sg) = w; }
; #pragma unroll
;         for (int rep = 0; rep < 2; ++rep) { const int it = tid + rep * 512; const int sq = (it & 15) | (((it >> 6) & 1) << 4), ko = ((it >> 4) & 3) | ((it >> 7) << 2);
;             const u32x4 r0 = kr[rep][0], r1 = kr[rep][1], r2 = kr[rep][2], r3 = kr[rep][3];
;             LAS bf16_t* dst = Kt + (ko * 8) * 136 + sq * 4;
;     ...
;             TRW(0, r0.x, r1.x, r2.x, r3.x, 0) TRW(1, r0.x, r1.x, r2.x, r3.x, 1) TRW(2, r0.y, r1.y, r2.y, r3.y, 0) TRW(3, r0.y, r1.y, r2.y, r3.y, 1)
;             TRW(4, r0.z, r1.z, r2.z, r3.z, 0) TRW(5, r0.z, r1.z, r2.z, r3.z, 1) TRW(6, r0.w, r1.w, r2.w, r3.w, 0) TRW(7, r0.w, r1.w, r2.w, r3.w, 1)
;     ...
;         }
;         __syncthreads();
;         if (st + 1 < 17) {
;             bool ic2; int ci2; const bf16_t* Kb2; const bf16_t* Vb2; passA_chunk(p, st + 1, b, h, dir, vs, ic2, ci2, Kb2, Vb2);
	v_mfma_f32_16x16x32_bf16 v[44:47], v[126:129], v[92:95], v[52:55]
	v_lshl_add_u32 v92, s34, 5, v56
	v_ashrrev_i32_e32 v93, 31, v92
	v_lshlrev_b64 v[92:93], 10, v[92:93]
	v_lshl_add_u64 v[94:95], v[92:93], 0, s[14:15]
	s_mov_b64 s[14:15], 0x4000
	v_mfma_f32_16x16x32_bf16 v[48:51], v[126:129], v[96:99], v[58:61]
	v_lshl_add_u64 v[96:97], v[92:93], 0, s[14:15]
	s_mov_b64 s[14:15], 0x6000
	v_lshl_add_u64 v[98:99], v[92:93], 0, s[14:15]
	s_cselect_b32 s15, s69, s13
	s_cselect_b32 s14, s68, s12
	s_add_u32 s41, s16, s10
	s_addc_u32 s46, s17, 0
	v_mfma_f32_16x16x32_bf16 v[52:55], v[126:129], v[114:117], v[130:133]
	v_and_b32_e32 v114, 24, v57
	s_add_u32 s16, s70, 0xfd20000
	v_lshlrev_b32_e32 v101, 1, v114
	v_mfma_f32_16x16x32_bf16 v[56:59], v[126:129], v[122:125], v[134:137]
	s_addc_u32 s17, s71, 0
	v_mul_u32_u24_e32 v115, 0x110, v100
	v_lshl_or_b32 v100, v100, 6, v101
	v_mfma_f32_16x16x32_bf16 v[60:63], v[126:129], v[118:121], v[138:141]
	v_mov_b32_e32 v101, v83
	v_lshl_add_u64 v[90:91], v[90:91], 2, s[16:17]
	v_lshlrev_b32_e32 v82, 2, v114
	v_lshl_add_u64 v[100:101], s[14:15], 0, v[100:101]
	v_lshl_add_u64 v[90:91], v[90:91], 0, v[82:83]
	s_add_u32 s14, s70, 0xfe20000
	v_lshlrev_b32_e32 v82, 5, v112
	s_movk_i32 s10, 0x180
	s_addc_u32 s15, s71, 0
	v_and_or_b32 v112, v111, s10, v82
	v_add_u32_e32 v111, v113, v115
	s_branch .LBB0_392

; __device__ __forceinline__ int opaque_tid() { int t = (int)threadIdx.x; asm volatile("" : "+v"(t)); return t; }
; #define PG8_STAGE(bufoff, gbase, voff) do { _Pragma("unroll") for (int _i = 0; _i < 2; ++_i) \
;         __builtin_amdgcn_global_load_lds((const unsigned*)((const char*)(gbase) + (voff)[_i]), (LAS unsigned*)(lds + (bufoff) + ldsw + _i * 8192), 16, 0, 0); } while (0)
; #define PG8_WAIT_V(n) asm volatile("s_waitcnt vmcnt(" #n ")" ::: "memory")
; #define PG8_BAR __builtin_amdgcn_s_barrier()
; template <class Epi, class Sched, bool ZERO>
; __device__ __forceinline__ void gemm_phase_acc(LAS unsigned char* lds, const Gemm g, const Sched& S, const Epi& E, f32x4 (&acc)[2][2][4][2]) {
;     const int tid = opaque_tid(), wid = __builtin_amdgcn_readfirstlane(tid >> 6), lane = tid & 63, wr = wid >> 2, wc = wid & 3, fr = lane & 15, fq = lane >> 4;
;     const int K = g.K, nt = K / BK;
;     unsigned voffA[2], voffB[2];
; #pragma unroll
;     for (int i = 0; i < 2; ++i) { int R, C; stage_rc(tid * 16 + i * 8192, R, C); const int Rb = (R & ~31) + perm32(R & 31);
;         voffA[i] = (unsigned)(R * K + C) * 2u; voffB[i] = (unsigned)(Rb * K + C) * 2u; }
;     const size_t kstep = (size_t)(BK * 2);
;     const size_t hstep = (size_t)HALF * K * 2;
;     const size_t tstep = 2 * hstep;
;     const unsigned ldsw = (unsigned)wid * 1024u;
;     const int aoff = lds_byte(wr * 64 + fr, fq * 8), boff = lds_byte(wc * 32 + fr, fq * 8);
;     ...
;     Unit cur, nxt; int ui = 0;
;     if (!S.next(0, cur)) return;
;     if constexpr (ZERO) {
; #pragma unroll
;     for (int a = 0; a < 2; ++a)
; #pragma unroll
;         for (int b = 0; b < 2; ++b)
; #pragma unroll
;             for (int m = 0; m < 4; ++m)
; #pragma unroll
;                 for (int n = 0; n < 2; ++n) acc[a][b][m][n] = (f32x4){0.f, 0.f, 0.f, 0.f};
;     }
;     bf16x8 At[4][2], B0[2][2], B1[2][2];
;     const char* cA = (const char*)g.A + (size_t)cur.pm * tstep; const char* cB = (const char*)g.Bt + (size_t)cur.pn * tstep;
;     PG8_STAGE(PG8_SB(0, 0), cB, voffB); PG8_STAGE(PG8_SA(0, 0), cA, voffA); PG8_STAGE(PG8_SB(0, 1), cB + hstep, voffB); PG8_STAGE(PG8_SA(0, 1), cA + hstep, voffA);
;     if (wr == 1) PG8_BAR;
;     PG8_WAIT_V(4); PG8_BAR;
;     PG8_STAGE(PG8_SB(1, 0), cB + kstep, voffB); PG8_STAGE(PG8_SA(1, 0), cA + kstep, voffA); PG8_STAGE(PG8_SB(1, 1), cB + hstep + kstep, voffB);
;     PG8_WAIT_V(6); PG8_BAR;
.LBB0_724:
	s_or_b64 exec, exec, s[0:1]
	s_waitcnt lgkmcnt(0)
	v_mov_b32_e32 v0, v224
	v_mov_b32_e32 v14, v224
	s_mov_b32 s0, 0x1fffe0
	v_ashrrev_i32_e32 v1, 31, v14
	v_lshrrev_b32_e32 v1, 26, v1
	v_add_u32_e32 v1, v14, v1
	v_ashrrev_i32_e32 v8, 6, v1
	v_bfe_i32 v1, v14, 27, 1
	v_lshlrev_b32_e32 v0, 4, v14
	v_lshrrev_b32_e32 v1, 22, v1
	v_add_u32_e32 v1, v0, v1
	v_and_b32_e32 v1, 0xfffffc00, v1
	v_sub_u32_e32 v1, v0, v1
	v_lshrrev_b32_e32 v2, 4, v1
	v_bitop3_b32 v2, v2, v1, 32 bitop3:0x6c
	v_ashrrev_i32_e32 v1, 31, v1
	v_lshrrev_b32_e32 v1, 26, v1
	v_add_u32_e32 v1, v2, v1
	v_ashrrev_i32_e32 v9, 6, v1
	v_lshlrev_b32_e32 v3, 3, v8
	v_mul_i32_i24_e32 v4, 64, v9
	v_and_b32_e32 v3, -16, v3
	v_sub_u32_e32 v2, v2, v4
	v_mov_b32_e32 v4, 1
	v_add_u32_e32 v1, v9, v3
	v_lshlrev_b32_e32 v3, 5, v8
	v_ashrrev_i16_sdwa v2, v4, sext(v2) dst_sel:DWORD dst_unused:UNUSED_PAD src0_sel:DWORD src1_sel:BYTE_0
	v_and_b32_e32 v3, 32, v3
	v_bfe_i32 v10, v2, 0, 16
	v_and_b32_e32 v6, 3, v9
	v_add_lshl_u32 v3, v3, v10, 1
	v_add_u32_e32 v0, 0x2000, v0
	v_lshlrev_b32_e32 v2, 1, v1
	v_lshrrev_b32_e32 v5, 2, v1
	v_and_or_b32 v6, v1, s0, v6
	v_lshl_add_u32 v160, v1, 11, v3
	v_ashrrev_i32_e32 v1, 31, v0
	v_lshrrev_b32_e32 v1, 22, v1
	v_add_u32_e32 v1, v0, v1
	v_ashrrev_i32_e32 v11, 10, v1
	v_mul_i32_i24_e32 v1, 0x400, v11
	v_sub_u32_e32 v0, v0, v1
	v_and_b32_e32 v2, 24, v2
	v_and_b32_e32 v5, 4, v5
	v_lshrrev_b32_e32 v1, 4, v0
	v_or3_b32 v2, v6, v5, v2
	v_bitop3_b32 v0, v1, v0, 32 bitop3:0x6c
	v_lshl_add_u32 v162, v2, 11, v3
	v_ashrrev_i32_e32 v2, 31, v0
	v_lshrrev_b32_e32 v2, 26, v2
	v_add_u32_e32 v2, v0, v2
	v_lshlrev_b32_e32 v1, 3, v11
	v_ashrrev_i32_e32 v12, 6, v2
	v_and_b32_e32 v2, 0xc0, v2
	v_and_b32_e32 v1, -16, v1
	v_sub_u32_e32 v0, v0, v2
	v_readfirstlane_b32 s27, v14
	v_add_u32_e32 v1, v12, v1
	v_ashrrev_i16_sdwa v0, v4, sext(v0) dst_sel:DWORD dst_unused:UNUSED_PAD src0_sel:DWORD src1_sel:BYTE_0
	v_and_b32_e32 v4, 3, v12
	s_ashr_i32 s1, s27, 6
	v_and_or_b32 v4, v1, s0, v4
	s_or_b32 s0, s34, 0x54
	s_ashr_i32 s2, s27, 8
	s_lshl_b32 s79, s1, 10
	s_lshl_b32 s3, s0, 19
	v_lshlrev_b32_e32 v3, 5, v11
	v_bfe_i32 v13, v0, 0, 16
	v_lshlrev_b32_e32 v0, 1, v1
	v_lshrrev_b32_e32 v2, 2, v1
	s_add_u32 s10, s70, s3
	v_and_b32_e32 v3, 32, v3
	v_and_b32_e32 v0, 24, v0
	v_and_b32_e32 v2, 4, v2
	s_addc_u32 s11, s71, 0
	s_add_i32 s80, s79, 0
	v_or3_b32 v0, v4, v2, v0
	v_add_lshl_u32 v2, v3, v13, 1
	s_add_i32 m0, s80, 0x10000
	v_lshl_add_u32 v166, v0, 11, v2
	global_load_lds_dwordx4 v162, s[10:11]
	s_add_i32 m0, s80, 0x12000
	s_add_i32 s81, s80, 0x2000
	global_load_lds_dwordx4 v166, s[10:11]
	s_mov_b32 m0, s80
	v_lshl_add_u32 v164, v1, 11, v2
	global_load_lds_dwordx4 v160, s[20:21]
	s_mov_b32 m0, s81
	s_add_u32 s4, s10, 0x40000
	global_load_lds_dwordx4 v164, s[20:21]
	s_addc_u32 s5, s11, 0
	s_add_i32 m0, s80, 0x14000
	s_add_i32 s82, s80, 0x4000
	global_load_lds_dwordx4 v162, s[4:5]
	s_add_i32 m0, s80, 0x16000
	s_add_i32 s83, s80, 0x6000
	global_load_lds_dwordx4 v166, s[4:5]
	s_mov_b32 m0, s82
	v_mov_b32_e32 v169, 0
	global_load_lds_dwordx4 v160, s[56:57]
	s_mov_b32 m0, s83
	v_mov_b32_e32 v163, v169
	global_load_lds_dwordx4 v164, s[56:57]
	v_mov_b32_e32 v167, v169
	v_mov_b32_e32 v161, v169
	v_mov_b32_e32 v165, v169
	s_mov_b32 s84, 0
	v_lshl_add_u64 v[6:7], s[10:11], 0, v[162:163]
	v_lshl_add_u64 v[4:5], s[10:11], 0, v[166:167]
	v_lshl_add_u64 v[2:3], s[20:21], 0, v[160:161]
	s_cmp_lg_u32 s2, 1
	v_lshl_add_u64 v[0:1], s[20:21], 0, v[164:165]
	s_cbranch_scc1 .LBB0_726
	s_barrier

; #define PG8_STAGE(bufoff, gbase, voff) do { _Pragma("unroll") for (int _i = 0; _i < 2; ++_i) \
;         __builtin_amdgcn_global_load_lds((const unsigned*)((const char*)(gbase) + (voff)[_i]), (LAS unsigned*)(lds + (bufoff) + ldsw + _i * 8192), 16, 0, 0); } while (0)
; #define PG8_LDA(dst, b, h) do { _Pragma("unroll") for (int m = 0; m < 4; ++m) _Pragma("unroll") for (int k = 0; k < 2; ++k) dst[m][k] = *(const LAS bf16x8*)(lds + PG8_SA(b, h) + aoff + m * 2048 + k * 1024); } while (0)
; #define PG8_LDB(dst, b, h) do { _Pragma("unroll") for (int n = 0; n < 2; ++n) _Pragma("unroll") for (int k = 0; k < 2; ++k) dst[n][k] = *(const LAS bf16x8*)(lds + PG8_SB(b, h) + boff + n * 2048 + k * 1024); } while (0)
; #define PG8_MMA(ai, bj, At, Bt) do { __builtin_amdgcn_s_setprio(1); _Pragma("unroll") for (int m = 0; m < 4; ++m) _Pragma("unroll") for (int n = 0; n < 2; ++n) _Pragma("unroll") for (int k = 0; k < 2; ++k) \
;         acc[ai][bj][m][n] = __builtin_amdgcn_mfma_f32_16x16x32_bf16(Bt[n][k], At[m][k], acc[ai][bj][m][n], 0, 0, 0); __builtin_amdgcn_s_setprio(0); } while (0)
; #define PG8_WAIT_L(n) asm volatile("s_waitcnt lgkmcnt(" #n ")" ::: "memory")
; #define PG8_BAR __builtin_amdgcn_s_barrier()
; #define PG8_SCHED __builtin_amdgcn_sched_barrier(0)
; template <class Epi, class Sched, bool ZERO>
; __device__ __forceinline__ void gemm_phase_acc(LAS unsigned char* lds, const Gemm g, const Sched& S, const Epi& E, f32x4 (&acc)[2][2][4][2]) {
;     ...
;             PG8_LDB(B0, 0, 0); PG8_SCHED; PG8_LDA(At, 0, 0); PG8_STAGE(PG8_SA(1, 1), a1 + hstep, voffA);
;             PG8_WAIT_L(8); PG8_BAR; PG8_WAIT_L(0); PG8_MMA(0, 0, At, B0); PG8_BAR; PG8_SCHED;
;             PG8_LDB(B1, 0, 1); PG8_STAGE(PG8_SB(0, 0), b2, voffB);
;             PG8_BAR; PG8_WAIT_L(0); PG8_MMA(0, 1, At, B1); PG8_BAR;
;             PG8_LDA(At, 0, 1); PG8_STAGE(PG8_SA(0, 0), a2, voffA);
;             PG8_BAR; PG8_WAIT_L(0); PG8_MMA(1, 0, At, B0); PG8_BAR; PG8_SCHED;
.LBB0_739:
	v_add_u32_e32 v76, s35, v191
	s_add_u32 s4, s20, s2
	ds_read_b128 v[40:43], v76
	ds_read_b128 v[52:55], v76 offset:1024
	ds_read_b128 v[64:67], v76 offset:2048
	ds_read_b128 v[76:79], v76 offset:3072
	s_addc_u32 s5, s21, s3
	s_add_u32 s4, s4, 0x100
	s_addc_u32 s5, s5, 0
	s_add_u32 s63, s60, s2
	s_addc_u32 s64, s61, s3
	s_cmpk_eq_i32 s2, 0x700
	s_cselect_b32 s7, s21, s5
	s_cselect_b32 s6, s20, s4
	s_cselect_b32 s5, s1, s64
	s_cselect_b32 s4, s39, s63
	v_lshl_add_u64 v[214:215], v[192:193], 0, s[2:3]
	s_add_i32 m0, s80, 0xc000
	ds_read_b128 v[80:83], v204
	ds_read_b128 v[92:95], v204 offset:1024
	ds_read_b128 v[104:107], v204 offset:2048
	ds_read_b128 v[116:119], v204 offset:3072
	ds_read_b128 v[196:199], v204 offset:4096
	ds_read_b128 v[200:203], v204 offset:5120
	ds_read_b128 v[206:209], v204 offset:6144
	ds_read_b128 v[210:213], v204 offset:7168
	global_load_lds_dwordx4 v[214:215], off
	v_lshl_add_u64 v[214:215], v[194:195], 0, s[2:3]
	s_add_i32 m0, s80, 0xe000
	s_nop 0
	global_load_lds_dwordx4 v[214:215], off
	s_waitcnt lgkmcnt(8)
	s_barrier
	s_waitcnt lgkmcnt(0)
	s_setprio 1
	s_waitcnt lgkmcnt(0)
	v_mfma_f32_16x16x32_bf16 v[156:159], v[40:43], v[80:83], v[156:159]
	v_mfma_f32_16x16x32_bf16 v[152:155], v[64:67], v[80:83], v[152:155]
	v_mfma_f32_16x16x32_bf16 v[140:143], v[40:43], v[104:107], v[140:143]
	v_mfma_f32_16x16x32_bf16 v[136:139], v[64:67], v[104:107], v[136:139]
	v_mfma_f32_16x16x32_bf16 v[124:127], v[40:43], v[196:199], v[124:127]
	v_mfma_f32_16x16x32_bf16 v[120:123], v[64:67], v[196:199], v[120:123]
	v_mfma_f32_16x16x32_bf16 v[100:103], v[40:43], v[206:209], v[100:103]
	v_mfma_f32_16x16x32_bf16 v[96:99], v[64:67], v[206:209], v[96:99]
	v_mfma_f32_16x16x32_bf16 v[156:159], v[52:55], v[92:95], v[156:159]
	v_mfma_f32_16x16x32_bf16 v[152:155], v[76:79], v[92:95], v[152:155]
	v_mfma_f32_16x16x32_bf16 v[140:143], v[52:55], v[116:119], v[140:143]
	v_mfma_f32_16x16x32_bf16 v[136:139], v[76:79], v[116:119], v[136:139]
	v_mfma_f32_16x16x32_bf16 v[124:127], v[52:55], v[200:203], v[124:127]
	v_mfma_f32_16x16x32_bf16 v[120:123], v[76:79], v[200:203], v[120:123]
	v_mfma_f32_16x16x32_bf16 v[100:103], v[52:55], v[210:213], v[100:103]
	v_mfma_f32_16x16x32_bf16 v[96:99], v[76:79], v[210:213], v[96:99]
	s_setprio 0
	s_barrier
	s_add_i32 s63, s35, s79
	v_add_u32_e32 v168, s22, v191
	v_lshl_add_u64 v[222:223], s[4:5], 0, v[162:163]
	s_mov_b32 m0, s63
	ds_read_b128 v[214:217], v168
	ds_read_b128 v[218:221], v168 offset:1024
	ds_read_b128 v[228:231], v168 offset:2048
	ds_read_b128 v[232:235], v168 offset:3072
	global_load_lds_dwordx4 v[222:223], off
	v_lshl_add_u64 v[244:245], s[4:5], 0, v[166:167]
	s_add_i32 m0, s63, 0x2000
	s_nop 0
	global_load_lds_dwordx4 v[244:245], off
	s_barrier
	s_waitcnt lgkmcnt(0)
	s_setprio 1
	s_waitcnt lgkmcnt(0)
	v_mfma_f32_16x16x32_bf16 v[148:151], v[214:217], v[80:83], v[148:151]
	v_mfma_f32_16x16x32_bf16 v[80:83], v[228:231], v[80:83], v[144:147]
	v_mfma_f32_16x16x32_bf16 v[112:115], v[214:217], v[196:199], v[112:115]
	v_mfma_f32_16x16x32_bf16 v[108:111], v[228:231], v[196:199], v[108:111]
	v_mfma_f32_16x16x32_bf16 v[88:91], v[214:217], v[206:209], v[88:91]
	v_mfma_f32_16x16x32_bf16 v[84:87], v[228:231], v[206:209], v[84:87]
	v_mfma_f32_16x16x32_bf16 v[148:151], v[218:221], v[92:95], v[148:151]
	v_mfma_f32_16x16x32_bf16 v[80:83], v[232:235], v[92:95], v[80:83]
	v_mfma_f32_16x16x32_bf16 v[92:95], v[214:217], v[104:107], v[132:135]
	v_mfma_f32_16x16x32_bf16 v[104:107], v[228:231], v[104:107], v[128:131]
	v_mfma_f32_16x16x32_bf16 v[112:115], v[218:221], v[200:203], v[112:115]
	v_mfma_f32_16x16x32_bf16 v[108:111], v[232:235], v[200:203], v[108:111]
	v_mfma_f32_16x16x32_bf16 v[88:91], v[218:221], v[210:213], v[88:91]
	v_mfma_f32_16x16x32_bf16 v[84:87], v[232:235], v[210:213], v[84:87]
	v_mfma_f32_16x16x32_bf16 v[92:95], v[218:221], v[116:119], v[92:95]
	v_mfma_f32_16x16x32_bf16 v[104:107], v[232:235], v[116:119], v[104:107]
	s_setprio 0
	s_mov_b32 m0, s80
	v_lshl_add_u64 v[246:247], s[6:7], 0, v[160:161]
	s_barrier
	ds_read_b128 v[116:119], v204 offset:16384
	ds_read_b128 v[128:131], v204 offset:17408
	ds_read_b128 v[132:135], v204 offset:18432
	ds_read_b128 v[144:147], v204 offset:19456
	ds_read_b128 v[196:199], v204 offset:20480
	ds_read_b128 v[200:203], v204 offset:21504
	ds_read_b128 v[206:209], v204 offset:22528
	ds_read_b128 v[210:213], v204 offset:23552
	global_load_lds_dwordx4 v[246:247], off
	v_lshl_add_u64 v[248:249], s[6:7], 0, v[164:165]
	s_mov_b32 m0, s81
	s_nop 0
	global_load_lds_dwordx4 v[248:249], off
	s_barrier
	s_waitcnt lgkmcnt(0)
	s_setprio 1
	s_waitcnt lgkmcnt(0)
	v_mfma_f32_16x16x32_bf16 v[72:75], v[40:43], v[116:119], v[72:75]
	v_mfma_f32_16x16x32_bf16 v[68:71], v[64:67], v[116:119], v[68:71]
	v_mfma_f32_16x16x32_bf16 v[48:51], v[40:43], v[132:135], v[48:51]
	v_mfma_f32_16x16x32_bf16 v[44:47], v[64:67], v[132:135], v[44:47]
	v_mfma_f32_16x16x32_bf16 v[28:31], v[40:43], v[196:199], v[28:31]
	v_mfma_f32_16x16x32_bf16 v[24:27], v[64:67], v[196:199], v[24:27]
	v_mfma_f32_16x16x32_bf16 v[12:15], v[40:43], v[206:209], v[12:15]
	v_mfma_f32_16x16x32_bf16 v[8:11], v[64:67], v[206:209], v[8:11]
	v_mfma_f32_16x16x32_bf16 v[72:75], v[52:55], v[128:131], v[72:75]
	v_mfma_f32_16x16x32_bf16 v[68:71], v[76:79], v[128:131], v[68:71]
	v_mfma_f32_16x16x32_bf16 v[48:51], v[52:55], v[144:147], v[48:51]
	v_mfma_f32_16x16x32_bf16 v[44:47], v[76:79], v[144:147], v[44:47]
	v_mfma_f32_16x16x32_bf16 v[28:31], v[52:55], v[200:203], v[28:31]
	v_mfma_f32_16x16x32_bf16 v[24:27], v[76:79], v[200:203], v[24:27]
	v_mfma_f32_16x16x32_bf16 v[12:15], v[52:55], v[210:213], v[12:15]
	v_mfma_f32_16x16x32_bf16 v[8:11], v[76:79], v[210:213], v[8:11]
	s_setprio 0
	s_barrier
; #define PG8_STAGE(bufoff, gbase, voff) do { _Pragma("unroll") for (int _i = 0; _i < 2; ++_i) \
;         __builtin_amdgcn_global_load_lds((const unsigned*)((const char*)(gbase) + (voff)[_i]), (LAS unsigned*)(lds + (bufoff) + ldsw + _i * 8192), 16, 0, 0); } while (0)
; #define PG8_LDA(dst, b, h) do { _Pragma("unroll") for (int m = 0; m < 4; ++m) _Pragma("unroll") for (int k = 0; k < 2; ++k) dst[m][k] = *(const LAS bf16x8*)(lds + PG8_SA(b, h) + aoff + m * 2048 + k * 1024); } while (0)
; #define PG8_LDB(dst, b, h) do { _Pragma("unroll") for (int n = 0; n < 2; ++n) _Pragma("unroll") for (int k = 0; k < 2; ++k) dst[n][k] = *(const LAS bf16x8*)(lds + PG8_SB(b, h) + boff + n * 2048 + k * 1024); } while (0)
; #define PG8_MMA(ai, bj, At, Bt) do { __builtin_amdgcn_s_setprio(1); _Pragma("unroll") for (int m = 0; m < 4; ++m) _Pragma("unroll") for (int n = 0; n < 2; ++n) _Pragma("unroll") for (int k = 0; k < 2; ++k) \
;         acc[ai][bj][m][n] = __builtin_amdgcn_mfma_f32_16x16x32_bf16(Bt[n][k], At[m][k], acc[ai][bj][m][n], 0, 0, 0); __builtin_amdgcn_s_setprio(0); } while (0)
; #define PG8_WAIT_V(n) asm volatile("s_waitcnt vmcnt(" #n ")" ::: "memory")
; #define PG8_WAIT_L(n) asm volatile("s_waitcnt lgkmcnt(" #n ")" ::: "memory")
; #define PG8_BAR __builtin_amdgcn_s_barrier()
; #define PG8_SCHED __builtin_amdgcn_sched_barrier(0)
; template <class Epi, class Sched, bool ZERO>
; __device__ __forceinline__ void gemm_phase_acc(LAS unsigned char* lds, const Gemm g, const Sched& S, const Epi& E, f32x4 (&acc)[2][2][4][2]) {
;     ...
;             PG8_STAGE(PG8_SB(0, 1), b2 + hstep, voffB);
;             PG8_WAIT_V(6); PG8_BAR; PG8_MMA(1, 1, At, B1); PG8_BAR;
;             PG8_LDB(B0, 1, 0); PG8_SCHED; PG8_LDA(At, 1, 0); PG8_STAGE(PG8_SA(0, 1), a2 + hstep, voffA);
;             PG8_WAIT_L(8); PG8_BAR; PG8_WAIT_L(0); PG8_MMA(0, 0, At, B0); PG8_BAR; PG8_SCHED;
;             PG8_LDB(B1, 1, 1); PG8_STAGE(PG8_SB(1, 0), b3, voffB);
;             PG8_BAR; PG8_WAIT_L(0); PG8_MMA(0, 1, At, B1); PG8_BAR;
	s_add_u32 s64, s4, 0x40000
	s_addc_u32 s65, s5, 0
	s_add_i32 s63, s22, s79
	v_lshl_add_u64 v[40:41], s[64:65], 0, v[162:163]
	s_mov_b32 m0, s63
	s_nop 0
	global_load_lds_dwordx4 v[40:41], off
	v_lshl_add_u64 v[40:41], s[64:65], 0, v[166:167]
	s_add_i32 m0, s63, 0x2000
	s_nop 0
	global_load_lds_dwordx4 v[40:41], off
	s_waitcnt vmcnt(6)
	s_barrier
	s_setprio 1
	v_mfma_f32_16x16x32_bf16 v[36:39], v[214:217], v[132:135], v[36:39]
	v_mfma_f32_16x16x32_bf16 v[32:35], v[228:231], v[132:135], v[32:35]
	v_mfma_f32_16x16x32_bf16 v[20:23], v[214:217], v[196:199], v[20:23]
	v_mfma_f32_16x16x32_bf16 v[16:19], v[228:231], v[196:199], v[16:19]
	v_mfma_f32_16x16x32_bf16 v[4:7], v[214:217], v[206:209], v[4:7]
	v_mfma_f32_16x16x32_bf16 v[0:3], v[228:231], v[206:209], v[0:3]
	v_mfma_f32_16x16x32_bf16 v[40:43], v[214:217], v[116:119], v[60:63]
	v_mfma_f32_16x16x32_bf16 v[52:55], v[228:231], v[116:119], v[56:59]
	v_mfma_f32_16x16x32_bf16 v[36:39], v[218:221], v[144:147], v[36:39]
	v_mfma_f32_16x16x32_bf16 v[32:35], v[232:235], v[144:147], v[32:35]
	v_mfma_f32_16x16x32_bf16 v[20:23], v[218:221], v[200:203], v[20:23]
	v_mfma_f32_16x16x32_bf16 v[16:19], v[232:235], v[200:203], v[16:19]
	v_mfma_f32_16x16x32_bf16 v[4:7], v[218:221], v[210:213], v[4:7]
	v_mfma_f32_16x16x32_bf16 v[0:3], v[232:235], v[210:213], v[0:3]
	v_mfma_f32_16x16x32_bf16 v[40:43], v[218:221], v[128:131], v[40:43]
	v_mfma_f32_16x16x32_bf16 v[52:55], v[232:235], v[128:131], v[52:55]
	s_setprio 0
	v_add_u32_e32 v76, s23, v191
	s_barrier
	ds_read_b128 v[56:59], v76
	ds_read_b128 v[60:63], v76 offset:1024
	ds_read_b128 v[64:67], v76 offset:2048
	ds_read_b128 v[76:79], v76 offset:3072
	s_add_u32 s6, s6, 0x40000
	s_addc_u32 s7, s7, 0
	s_mov_b32 m0, s82
	v_lshl_add_u64 v[132:133], s[6:7], 0, v[160:161]
	ds_read_b128 v[116:119], v204 offset:32768
	ds_read_b128 v[128:131], v204 offset:33792
	ds_read_b128 v[196:199], v204 offset:34816
	ds_read_b128 v[200:203], v204 offset:35840
	ds_read_b128 v[206:209], v204 offset:36864
	ds_read_b128 v[210:213], v204 offset:37888
	ds_read_b128 v[214:217], v204 offset:38912
	ds_read_b128 v[218:221], v204 offset:39936
	global_load_lds_dwordx4 v[132:133], off
	v_lshl_add_u64 v[132:133], s[6:7], 0, v[164:165]
	s_mov_b32 m0, s83
	s_nop 0
	global_load_lds_dwordx4 v[132:133], off
	s_waitcnt lgkmcnt(8)
	s_barrier
	s_waitcnt lgkmcnt(0)
	s_setprio 1
	s_waitcnt lgkmcnt(0)
	v_mfma_f32_16x16x32_bf16 v[132:135], v[56:59], v[116:119], v[156:159]
	v_mfma_f32_16x16x32_bf16 v[156:159], v[60:63], v[128:131], v[132:135]
	v_mfma_f32_16x16x32_bf16 v[132:135], v[64:67], v[116:119], v[152:155]
	v_mfma_f32_16x16x32_bf16 v[152:155], v[76:79], v[128:131], v[132:135]
	v_mfma_f32_16x16x32_bf16 v[132:135], v[56:59], v[196:199], v[140:143]
	v_mfma_f32_16x16x32_bf16 v[140:143], v[60:63], v[200:203], v[132:135]
	v_mfma_f32_16x16x32_bf16 v[132:135], v[64:67], v[196:199], v[136:139]
	v_mfma_f32_16x16x32_bf16 v[124:127], v[56:59], v[206:209], v[124:127]
	v_mfma_f32_16x16x32_bf16 v[120:123], v[64:67], v[206:209], v[120:123]
	v_mfma_f32_16x16x32_bf16 v[100:103], v[56:59], v[214:217], v[100:103]
	v_mfma_f32_16x16x32_bf16 v[96:99], v[64:67], v[214:217], v[96:99]
	v_mfma_f32_16x16x32_bf16 v[136:139], v[76:79], v[200:203], v[132:135]
	v_mfma_f32_16x16x32_bf16 v[124:127], v[60:63], v[210:213], v[124:127]
	v_mfma_f32_16x16x32_bf16 v[120:123], v[76:79], v[210:213], v[120:123]
	v_mfma_f32_16x16x32_bf16 v[100:103], v[60:63], v[218:221], v[100:103]
	v_mfma_f32_16x16x32_bf16 v[96:99], v[76:79], v[218:221], v[96:99]
	s_setprio 0
	s_barrier
	v_add_u32_e32 v132, s33, v191
	s_add_i32 s6, s23, s79
	ds_read_b128 v[228:231], v132
	ds_read_b128 v[232:235], v132 offset:1024
	ds_read_b128 v[236:239], v132 offset:2048
	ds_read_b128 v[240:243], v132 offset:3072
	v_lshl_add_u64 v[132:133], v[222:223], 0, s[8:9]
	s_mov_b32 m0, s6
	s_nop 0
	global_load_lds_dwordx4 v[132:133], off
	v_lshl_add_u64 v[132:133], v[244:245], 0, s[8:9]
	s_add_i32 m0, s6, 0x2000
	s_nop 0
	global_load_lds_dwordx4 v[132:133], off
	s_barrier
; #define PG8_STAGE(bufoff, gbase, voff) do { _Pragma("unroll") for (int _i = 0; _i < 2; ++_i) \
;         __builtin_amdgcn_global_load_lds((const unsigned*)((const char*)(gbase) + (voff)[_i]), (LAS unsigned*)(lds + (bufoff) + ldsw + _i * 8192), 16, 0, 0); } while (0)
; #define PG8_LDA(dst, b, h) do { _Pragma("unroll") for (int m = 0; m < 4; ++m) _Pragma("unroll") for (int k = 0; k < 2; ++k) dst[m][k] = *(const LAS bf16x8*)(lds + PG8_SA(b, h) + aoff + m * 2048 + k * 1024); } while (0)
; #define PG8_MMA(ai, bj, At, Bt) do { __builtin_amdgcn_s_setprio(1); _Pragma("unroll") for (int m = 0; m < 4; ++m) _Pragma("unroll") for (int n = 0; n < 2; ++n) _Pragma("unroll") for (int k = 0; k < 2; ++k) \
;         acc[ai][bj][m][n] = __builtin_amdgcn_mfma_f32_16x16x32_bf16(Bt[n][k], At[m][k], acc[ai][bj][m][n], 0, 0, 0); __builtin_amdgcn_s_setprio(0); } while (0)
; #define PG8_WAIT_V(n) asm volatile("s_waitcnt vmcnt(" #n ")" ::: "memory")
; #define PG8_WAIT_L(n) asm volatile("s_waitcnt lgkmcnt(" #n ")" ::: "memory")
; #define PG8_BAR __builtin_amdgcn_s_barrier()
; #define PG8_SCHED __builtin_amdgcn_sched_barrier(0)
; template <class Epi, class Sched, bool ZERO>
; __device__ __forceinline__ void gemm_phase_acc(LAS unsigned char* lds, const Gemm g, const Sched& S, const Epi& E, f32x4 (&acc)[2][2][4][2]) {
;     ...
;             PG8_BAR; PG8_WAIT_L(0); PG8_MMA(0, 1, At, B1); PG8_BAR;
;             PG8_LDA(At, 1, 1); PG8_STAGE(PG8_SA(1, 0), a3, voffA);
;             PG8_BAR; PG8_WAIT_L(0); PG8_MMA(1, 0, At, B0); PG8_BAR; PG8_SCHED;
;             PG8_STAGE(PG8_SB(1, 1), b3 + hstep, voffB);
;             PG8_WAIT_V(6); PG8_BAR; PG8_MMA(1, 1, At, B1); PG8_BAR;
;         }
;         if constexpr (!Epi::AFTER_DRAIN) E(acc, cur, wr, wc, fr, fq);
;         if constexpr (Epi::DRAIN) __builtin_amdgcn_s_waitcnt(0x0F70);
;         if (!has_next) break;
	s_waitcnt lgkmcnt(0)
	s_setprio 1
	s_waitcnt lgkmcnt(0)
	v_mfma_f32_16x16x32_bf16 v[80:83], v[236:239], v[116:119], v[80:83]
	v_mfma_f32_16x16x32_bf16 v[132:135], v[228:231], v[116:119], v[148:151]
	v_mfma_f32_16x16x32_bf16 v[144:147], v[240:243], v[128:131], v[80:83]
	v_mfma_f32_16x16x32_bf16 v[80:83], v[228:231], v[196:199], v[92:95]
	v_mfma_f32_16x16x32_bf16 v[148:151], v[232:235], v[128:131], v[132:135]
	v_mfma_f32_16x16x32_bf16 v[132:135], v[232:235], v[200:203], v[80:83]
	v_mfma_f32_16x16x32_bf16 v[80:83], v[236:239], v[196:199], v[104:107]
	v_mfma_f32_16x16x32_bf16 v[128:131], v[240:243], v[200:203], v[80:83]
	v_mfma_f32_16x16x32_bf16 v[80:83], v[228:231], v[206:209], v[112:115]
	v_mfma_f32_16x16x32_bf16 v[112:115], v[232:235], v[210:213], v[80:83]
	v_mfma_f32_16x16x32_bf16 v[80:83], v[236:239], v[206:209], v[108:111]
	v_mfma_f32_16x16x32_bf16 v[108:111], v[240:243], v[210:213], v[80:83]
	v_mfma_f32_16x16x32_bf16 v[80:83], v[228:231], v[214:217], v[88:91]
	v_mfma_f32_16x16x32_bf16 v[88:91], v[232:235], v[218:221], v[80:83]
	v_mfma_f32_16x16x32_bf16 v[80:83], v[236:239], v[214:217], v[84:87]
	v_mfma_f32_16x16x32_bf16 v[84:87], v[240:243], v[218:221], v[80:83]
	s_setprio 0
	s_mov_b32 m0, s85
	v_lshl_add_u64 v[214:215], v[246:247], 0, s[8:9]
	s_barrier
	s_nop 2
	ds_read_b128 v[80:83], v204 offset:49152
	ds_read_b128 v[92:95], v204 offset:50176
	ds_read_b128 v[104:107], v204 offset:51200
	ds_read_b128 v[116:119], v204 offset:52224
	ds_read_b128 v[196:199], v204 offset:53248
	ds_read_b128 v[200:203], v204 offset:54272
	ds_read_b128 v[206:209], v204 offset:55296
	ds_read_b128 v[210:213], v204 offset:56320
	global_load_lds_dwordx4 v[214:215], off
	v_lshl_add_u64 v[214:215], v[248:249], 0, s[8:9]
	s_mov_b32 m0, s86
	s_nop 0
	global_load_lds_dwordx4 v[214:215], off
	s_barrier
	s_waitcnt lgkmcnt(0)
	s_setprio 1
	s_waitcnt lgkmcnt(0)
	v_mfma_f32_16x16x32_bf16 v[72:75], v[56:59], v[80:83], v[72:75]
	v_mfma_f32_16x16x32_bf16 v[68:71], v[64:67], v[80:83], v[68:71]
	v_mfma_f32_16x16x32_bf16 v[48:51], v[56:59], v[104:107], v[48:51]
	v_mfma_f32_16x16x32_bf16 v[44:47], v[64:67], v[104:107], v[44:47]
	v_mfma_f32_16x16x32_bf16 v[28:31], v[56:59], v[196:199], v[28:31]
	v_mfma_f32_16x16x32_bf16 v[24:27], v[64:67], v[196:199], v[24:27]
	v_mfma_f32_16x16x32_bf16 v[12:15], v[56:59], v[206:209], v[12:15]
	v_mfma_f32_16x16x32_bf16 v[8:11], v[64:67], v[206:209], v[8:11]
	v_mfma_f32_16x16x32_bf16 v[72:75], v[60:63], v[92:95], v[72:75]
	v_mfma_f32_16x16x32_bf16 v[68:71], v[76:79], v[92:95], v[68:71]
	v_mfma_f32_16x16x32_bf16 v[48:51], v[60:63], v[116:119], v[48:51]
	v_mfma_f32_16x16x32_bf16 v[44:47], v[76:79], v[116:119], v[44:47]
	v_mfma_f32_16x16x32_bf16 v[28:31], v[60:63], v[200:203], v[28:31]
	v_mfma_f32_16x16x32_bf16 v[24:27], v[76:79], v[200:203], v[24:27]
	v_mfma_f32_16x16x32_bf16 v[12:15], v[60:63], v[210:213], v[12:15]
	v_mfma_f32_16x16x32_bf16 v[8:11], v[76:79], v[210:213], v[8:11]
	s_setprio 0
	s_barrier
	s_add_u32 s4, s4, 0x40080
	s_addc_u32 s5, s5, 0
	s_add_i32 s6, s33, s79
	v_lshl_add_u64 v[56:57], s[4:5], 0, v[162:163]
	s_mov_b32 m0, s6
	s_nop 0
	global_load_lds_dwordx4 v[56:57], off
	v_lshl_add_u64 v[56:57], s[4:5], 0, v[166:167]
	s_add_i32 m0, s6, 0x2000
	s_nop 0
	global_load_lds_dwordx4 v[56:57], off
	s_waitcnt vmcnt(6)
	s_barrier
	s_setprio 1
	v_mfma_f32_16x16x32_bf16 v[40:43], v[228:231], v[80:83], v[40:43]
	v_mfma_f32_16x16x32_bf16 v[60:63], v[232:235], v[92:95], v[40:43]
	v_mfma_f32_16x16x32_bf16 v[40:43], v[236:239], v[80:83], v[52:55]
	v_mfma_f32_16x16x32_bf16 v[36:39], v[228:231], v[104:107], v[36:39]
	v_mfma_f32_16x16x32_bf16 v[32:35], v[236:239], v[104:107], v[32:35]
	v_mfma_f32_16x16x32_bf16 v[20:23], v[228:231], v[196:199], v[20:23]
	v_mfma_f32_16x16x32_bf16 v[16:19], v[236:239], v[196:199], v[16:19]
	v_mfma_f32_16x16x32_bf16 v[4:7], v[228:231], v[206:209], v[4:7]
	v_mfma_f32_16x16x32_bf16 v[0:3], v[236:239], v[206:209], v[0:3]
	v_mfma_f32_16x16x32_bf16 v[56:59], v[240:243], v[92:95], v[40:43]
	v_mfma_f32_16x16x32_bf16 v[36:39], v[232:235], v[116:119], v[36:39]
	v_mfma_f32_16x16x32_bf16 v[32:35], v[240:243], v[116:119], v[32:35]
	v_mfma_f32_16x16x32_bf16 v[20:23], v[232:235], v[200:203], v[20:23]
	v_mfma_f32_16x16x32_bf16 v[16:19], v[240:243], v[200:203], v[16:19]
	v_mfma_f32_16x16x32_bf16 v[4:7], v[232:235], v[210:213], v[4:7]
	v_mfma_f32_16x16x32_bf16 v[0:3], v[240:243], v[210:213], v[0:3]
	s_setprio 0
	s_add_i32 s62, s62, 2
	s_add_u32 s2, s2, 0x100
	s_addc_u32 s3, s3, 0
	s_cmp_gt_u32 s62, 13
	s_barrier
	s_cbranch_scc0 .LBB0_739
	s_cmp_lg_u32 s84, 0
	s_cbranch_scc1 .Lgb4_skip
	v_cmp_eq_u32_e32 vcc, 0, v224
	s_and_saveexec_b64 s[94:95], vcc
	s_cbranch_execz .Lgb4_done
	s_add_u32 s90, s70, 0xff83500
	s_addc_u32 s91, s71, 0
	s_mov_b32 s92, 0x8000
	v_mov_b32_e32 v250, 0
.Lgb4_spin:
	global_load_dword v251, v250, s[90:91] sc1
	s_waitcnt vmcnt(0)
	v_readfirstlane_b32 s93, v251
	s_cmp_ge_u32 s93, 4
	s_cbranch_scc1 .Lgb4_ok
	s_sleep 1
	s_sub_u32 s92, s92, 1
	s_cmp_lg_u32 s92, 0
	s_cbranch_scc1 .Lgb4_spin

;     __device__ __forceinline__ void operator()(const f32x4 (&acc)[2][2][4][2], const Unit& u, int wr, int wc, int fr, int fq) const {
;         const int wt = u.pn - 72;
;         const int gl_off = ((wr * 4 + wc) * 16 * 64 + (fq * 16 + fr)) * 8;
;         const int row0 = u.pm * 256 + wr * 64 + fr, col0 = wc * 32 + 8 * fq;
;         const bf16_t* ldp = nullptr; bf16_t* stp; bool ld_lm = false, st_lm = false, act_silu = false, recip = false; int ld = 0;
;         if (wt < 16) { bf16_t* t = (bf16_t*)(ws + OFF_Q) + (size_t)(u.pm * 4 + (wt - 12)) * 65536 + gl_off; ldp = t; stp = t; ld_lm = st_lm = true; }
;         else if (wt < 20) { ldp = (const bf16_t*)(ws + OFF_Q) + (size_t)(u.pm * 4 + (wt - 16)) * 65536 + gl_off; ld_lm = true; stp = am + (wt - 16) * 256; ld = 1024; act_silu = true; }
;         else if (wt < 24) { bf16_t* t = (bf16_t*)(ws + OFF_PM) + (wt - 22) * 256; ldp = t; stp = t; ld = 512; act_silu = true; }
;         else if (wt < 28) { stp = (bf16_t*)(ws + OFF_GB) + (size_t)(u.pm * 8 + (wt - 24)) * 65536 + gl_off; st_lm = true; }
;         else { bf16_t* t = (bf16_t*)(ws + OFF_GB) + (size_t)(u.pm * 8 + (wt - 24)) * 65536 + gl_off; stp = t; st_lm = true; ldp = t - 4 * 65536; ld_lm = true; recip = true; }
.Lgb4_done:
	s_or_b64 exec, exec, s[94:95]
	s_barrier
.Lgb4_skip:
	s_cmpk_gt_i32 s38, 0x57
	s_mov_b64 s[2:3], -1
	s_cbranch_scc0 .LBB0_750
	s_cmpk_gt_u32 s38, 0x5b
	s_cbranch_scc0 .LBB0_747
	s_mov_b64 s[4:5], -1
	s_cmpk_gt_u32 s38, 0x5f
	s_mov_b64 s[6:7], -1
	s_cbranch_scc0 .LBB0_745
	s_add_i32 s2, s87, s38
	s_ashr_i32 s3, s2, 31
	s_lshl_b64 s[2:3], s[2:3], 17
	s_cmpk_lt_u32 s38, 0x64
	v_lshl_add_u64 v[196:197], v[174:175], 0, s[2:3]
	s_mov_b64 s[6:7], 0
	v_mov_b64_e32 v[198:199], 0
	s_mov_b64 s[64:65], 0
	s_cbranch_scc1 .LBB0_745
	s_mov_b32 s2, 0xfff80000
	s_mov_b32 s3, -1
	v_lshl_add_u64 v[198:199], v[196:197], 0, s[2:3]
	s_mov_b64 s[64:65], -1
